# speedup vs baseline: 1.0132x; 1.0132x over previous
; #define LAS __attribute__((address_space(3)))
; template <int NCH, class RB, class EP>
; __device__ __forceinline__ void tail_gemm(const bf16* A16, const bf16* Bt, int K, int ngroups, int vcu, int G, LAS unsigned char* lds, int wave, RB rb, EP ep) {
;     ...
;         for (int k = 0; k < kw; k += 32) {
;             const bf16x8 av = *(const bf16x8*)(ap + k);
; #pragma unroll
;             for (int c = 0; c < NCH; ++c) { const bf16x8 bv = *(const bf16x8*)(Bt + (size_t)(rb(g, c) + r) * K + wave * kw + 8 * q + k);
;                 acc[c] = __builtin_amdgcn_mfma_f32_16x16x32_bf16(av, bv, acc[c], 0, 0, 0); }
;         }
; #pragma unroll
;         for (int c = 0; c < NCH; ++c) *(LAS f32x4*)(red + (wave * NCH + c) * 256 + lane * 4) = acc[c];
;         __syncthreads();
;         if (tid < 256) {
;             float v[NCH];
; #pragma unroll
;             for (int c = 0; c < NCH; ++c) { float s = 0.f;
; #pragma unroll
;                 for (int w = 0; w < 8; ++w) s += red[(w * NCH + c) * 256 + tid];
;                 v[c] = s; }
;             ep(g, 4 * (tid >> 6) + (tid & 3), (tid >> 2) & 15, v);
;         }
;         __syncthreads();
;     }
; }
; __global__ void __launch_bounds__(NTHR, 2) mk_fwd(Args a_byval) {
;     ...
;                 { float* H = (float*)(ws + WS_H); float* OUT = l == DEPTH - 1 ? a->out : nullptr;
;                   tail_gemm<1>((const bf16*)(ws + WS_ACT) + (size_t)8192 * DFF, (const bf16*)(wl + OFF_WDN), DFF, DM / 16, vcu, G, lds, wave0,
;                       [](int g, int) { return g * 16; }, [=](int g, int r, int c, const float* v) { const float nv = H[(size_t)(8192 + r) * DM + g * 16 + c] + v[0];
;                           if (OUT) OUT[(size_t)(8192 + r - NMETA) * DM + g * 16 + c] = nv; else H[(size_t)(8192 + r) * DM + g * 16 + c] = nv; }); }
.LBB0_30:
	v_lshl_add_u64 v[18:19], v[12:13], 0, v[148:149]
	v_add_co_u32_e32 v26, vcc, 0x24390000, v18
	v_lshl_add_u64 v[22:23], v[12:13], 0, v[10:11]
	s_nop 0
	v_addc_co_u32_e32 v27, vcc, 0, v19, vcc
	v_add_co_u32_e32 v28, vcc, 0x4680000, v22
	s_nop 1
	v_addc_co_u32_e32 v29, vcc, 0, v23, vcc
	global_load_dwordx4 v[64:67], v[26:27], off
	global_load_dwordx4 v[68:71], v[28:29], off
	global_load_dwordx4 v[72:75], v[26:27], off offset:64
	global_load_dwordx4 v[76:79], v[28:29], off offset:64
	global_load_dwordx4 v[80:83], v[26:27], off offset:128
	global_load_dwordx4 v[84:87], v[28:29], off offset:128
	global_load_dwordx4 v[88:91], v[26:27], off offset:192
	global_load_dwordx4 v[92:95], v[28:29], off offset:192
	global_load_dwordx4 v[96:99], v[26:27], off offset:256
	global_load_dwordx4 v[100:103], v[28:29], off offset:256
	global_load_dwordx4 v[104:107], v[26:27], off offset:320
	global_load_dwordx4 v[108:111], v[28:29], off offset:320
	global_load_dwordx4 v[112:115], v[26:27], off offset:384
	global_load_dwordx4 v[116:119], v[28:29], off offset:384
	global_load_dwordx4 v[120:123], v[26:27], off offset:448
	global_load_dwordx4 v[124:127], v[28:29], off offset:448
	global_load_dwordx4 v[156:159], v[26:27], off offset:512
	global_load_dwordx4 v[160:163], v[28:29], off offset:512
	global_load_dwordx4 v[164:167], v[26:27], off offset:576
	global_load_dwordx4 v[168:171], v[28:29], off offset:576
	global_load_dwordx4 v[172:175], v[26:27], off offset:640
	global_load_dwordx4 v[176:179], v[28:29], off offset:640
	global_load_dwordx4 v[180:183], v[26:27], off offset:704
	global_load_dwordx4 v[184:187], v[28:29], off offset:704
	global_load_dwordx4 v[188:191], v[26:27], off offset:768
	global_load_dwordx4 v[208:211], v[28:29], off offset:768
	global_load_dwordx4 v[212:215], v[26:27], off offset:832
	global_load_dwordx4 v[216:219], v[28:29], off offset:832
	global_load_dwordx4 v[220:223], v[26:27], off offset:896
	global_load_dwordx4 v[224:227], v[28:29], off offset:896
	s_waitcnt vmcnt(28)
	v_mfma_f32_16x16x32_bf16 v[0:3], v[64:67], v[68:71], v[0:3]
	global_load_dwordx4 v[64:67], v[26:27], off offset:960
	global_load_dwordx4 v[68:71], v[28:29], off offset:960
	s_waitcnt vmcnt(28)
	v_mfma_f32_16x16x32_bf16 v[0:3], v[72:75], v[76:79], v[0:3]
	global_load_dwordx4 v[72:75], v[26:27], off offset:1024
	global_load_dwordx4 v[76:79], v[28:29], off offset:1024
	s_waitcnt vmcnt(28)
	v_mfma_f32_16x16x32_bf16 v[0:3], v[80:83], v[84:87], v[0:3]
	global_load_dwordx4 v[80:83], v[26:27], off offset:1088
	global_load_dwordx4 v[84:87], v[28:29], off offset:1088
	s_waitcnt vmcnt(28)
	v_mfma_f32_16x16x32_bf16 v[0:3], v[88:91], v[92:95], v[0:3]
	global_load_dwordx4 v[88:91], v[26:27], off offset:1152
	global_load_dwordx4 v[92:95], v[28:29], off offset:1152
	s_waitcnt vmcnt(28)
	v_mfma_f32_16x16x32_bf16 v[0:3], v[96:99], v[100:103], v[0:3]
	global_load_dwordx4 v[96:99], v[26:27], off offset:1216
	global_load_dwordx4 v[100:103], v[28:29], off offset:1216
	s_waitcnt vmcnt(28)
	v_mfma_f32_16x16x32_bf16 v[0:3], v[104:107], v[108:111], v[0:3]
	global_load_dwordx4 v[104:107], v[26:27], off offset:1280
	global_load_dwordx4 v[108:111], v[28:29], off offset:1280
	s_waitcnt vmcnt(28)
	v_mfma_f32_16x16x32_bf16 v[0:3], v[112:115], v[116:119], v[0:3]
	global_load_dwordx4 v[112:115], v[26:27], off offset:1344
	global_load_dwordx4 v[116:119], v[28:29], off offset:1344
	s_waitcnt vmcnt(28)
	v_mfma_f32_16x16x32_bf16 v[0:3], v[120:123], v[124:127], v[0:3]
	s_waitcnt vmcnt(26)
	v_mfma_f32_16x16x32_bf16 v[0:3], v[156:159], v[160:163], v[0:3]
	s_waitcnt vmcnt(24)
	v_mfma_f32_16x16x32_bf16 v[0:3], v[164:167], v[168:171], v[0:3]
	s_waitcnt vmcnt(22)
	v_mfma_f32_16x16x32_bf16 v[0:3], v[172:175], v[176:179], v[0:3]
	s_waitcnt vmcnt(20)
	v_mfma_f32_16x16x32_bf16 v[0:3], v[180:183], v[184:187], v[0:3]
	s_waitcnt vmcnt(18)
	v_mfma_f32_16x16x32_bf16 v[0:3], v[188:191], v[208:211], v[0:3]
	s_waitcnt vmcnt(16)
	v_mfma_f32_16x16x32_bf16 v[0:3], v[212:215], v[216:219], v[0:3]
	s_waitcnt vmcnt(14)
	v_mfma_f32_16x16x32_bf16 v[0:3], v[220:223], v[224:227], v[0:3]
	s_waitcnt vmcnt(12)
	v_mfma_f32_16x16x32_bf16 v[0:3], v[64:67], v[68:71], v[0:3]
	s_waitcnt vmcnt(10)
	v_mfma_f32_16x16x32_bf16 v[0:3], v[72:75], v[76:79], v[0:3]
	s_waitcnt vmcnt(8)
	v_mfma_f32_16x16x32_bf16 v[0:3], v[80:83], v[84:87], v[0:3]
	s_waitcnt vmcnt(6)
	v_mfma_f32_16x16x32_bf16 v[0:3], v[88:91], v[92:95], v[0:3]
	s_waitcnt vmcnt(4)
	v_mfma_f32_16x16x32_bf16 v[0:3], v[96:99], v[100:103], v[0:3]
	s_waitcnt vmcnt(2)
	v_mfma_f32_16x16x32_bf16 v[0:3], v[104:107], v[108:111], v[0:3]
	s_waitcnt vmcnt(0)
	v_mfma_f32_16x16x32_bf16 v[0:3], v[112:115], v[116:119], v[0:3]
	s_nop 3
	s_nop 6
	ds_write_b128 v14, v[0:3]
	s_waitcnt lgkmcnt(0)
	s_barrier
	s_and_saveexec_b64 s[22:23], s[40:41]
	s_cbranch_execz .LBB0_28
	ds_read2st64_b32 v[0:1], v15 offset1:4
	s_lshl_b32 s42, s7, 4
	s_ashr_i32 s43, s42, 31
	s_and_b64 vcc, exec, s[20:21]
	s_waitcnt lgkmcnt(0)
	v_add_f32_e32 v0, 0, v0
	v_add_f32_e32 v2, v0, v1
	ds_read2st64_b32 v[0:1], v15 offset0:8 offset1:12
	s_waitcnt lgkmcnt(0)
	v_add_f32_e32 v0, v2, v0
	v_add_f32_e32 v2, v0, v1
	ds_read2st64_b32 v[0:1], v15 offset0:16 offset1:20
	s_waitcnt lgkmcnt(0)
	v_add_f32_e32 v0, v2, v0
	v_add_f32_e32 v2, v0, v1
	ds_read2st64_b32 v[0:1], v15 offset0:24 offset1:28
	s_waitcnt lgkmcnt(0)
	v_add_f32_e32 v0, v2, v0
	v_add_f32_e32 v2, v0, v1
	v_lshl_add_u64 v[0:1], s[42:43], 2, v[4:5]
	global_load_dword v3, v[0:1], off
	s_waitcnt vmcnt(0)
	v_add_f32_e32 v2, v2, v3
	s_cbranch_vccz .LBB0_34
	v_lshl_add_u64 v[10:11], s[42:43], 2, v[6:7]
	global_store_dword v[10:11], v2, off
	s_cbranch_execnz .LBB0_28
	s_branch .LBB0_27

;     __device__ __forceinline__ void operator()(const f32x4 (&acc)[2][2][4][2], const pg8::Unit& u, int wr, int wc, int fr, int fq) const {
;         const int row0 = u.pm * 256 + wr * 64 + fr, col0 = u.pn * 256 + wc * 32 + 4 * fq;
; #pragma unroll
;         for (int ai = 0; ai < 2; ++ai)
; #pragma unroll
;             for (int m = 0; m < 4; ++m) {
;                 const int row = row0 + ai * 128 + m * 16;
;                 float* rp = H + (size_t)row * DM + col0;
;                 float* op = OUT ? (OUT + (size_t)(row - NMETA) * DM + col0) : rp;
;                 const bool wr_ok = OUT ? (row >= NMETA && row < T_) : true;
; #pragma unroll
;                 for (int bj = 0; bj < 2; ++bj)
; #pragma unroll
;                     for (int n = 0; n < 2; ++n) {
;                         const f32x4 v = *(const f32x4*)(rp + bj * 128 + n * 16) + acc[ai][bj][m][n];
;                         if (wr_ok) __builtin_nontemporal_store(v, (f32x4*)(op + bj * 128 + n * 16));
;                     }
.LBB0_56:
	s_lshl_b32 s5, s39, 8
	s_add_i32 s5, s5, s76
	v_or_b32_e32 v136, s5, v142
	v_lshl_or_b32 v134, s38, 8, v144
	s_movk_i32 s0, 0x2000
	v_ashrrev_i32_e32 v135, 31, v134
	v_readlane_b32 s66, v255, 8
	v_lshlrev_b64 v[134:135], 2, v[134:135]
	v_mov_b32_e32 v150, v136
	v_ashrrev_i32_e32 v151, 31, v150
	v_lshlrev_b64 v[150:151], 13, v[150:151]
	v_lshl_add_u64 v[150:151], s[52:53], 0, v[150:151]
	v_add_u32_e32 v152, -16, v136
	v_ashrrev_i32_e32 v153, 31, v152
	v_lshlrev_b64 v[152:153], 13, v[152:153]
	v_lshl_add_u64 v[152:153], s[48:49], 0, v[152:153]
	v_cndmask_b32_e64 v153, v153, v151, s[40:41]
	v_cndmask_b32_e64 v152, v152, v150, s[40:41]
	v_lshl_add_u64 v[150:151], v[150:151], 0, v[134:135]
	v_lshl_add_u64 v[222:223], v[152:153], 0, v[134:135]
	global_load_dwordx4 v[156:159], v[150:151], off
	global_load_dwordx4 v[160:163], v[150:151], off offset:64
	global_load_dwordx4 v[164:167], v[150:151], off offset:512
	global_load_dwordx4 v[168:171], v[150:151], off offset:576
	v_add_u32_e32 v150, 16, v136
	v_ashrrev_i32_e32 v151, 31, v150
	v_lshlrev_b64 v[150:151], 13, v[150:151]
	v_lshl_add_u64 v[150:151], s[52:53], 0, v[150:151]
	v_add_u32_e32 v152, 0, v136
	v_ashrrev_i32_e32 v153, 31, v152
	v_lshlrev_b64 v[152:153], 13, v[152:153]
	v_lshl_add_u64 v[152:153], s[48:49], 0, v[152:153]
	v_cndmask_b32_e64 v153, v153, v151, s[40:41]
	v_cndmask_b32_e64 v152, v152, v150, s[40:41]
	v_lshl_add_u64 v[150:151], v[150:151], 0, v[134:135]
	v_lshl_add_u64 v[224:225], v[152:153], 0, v[134:135]
	global_load_dwordx4 v[172:175], v[150:151], off
	global_load_dwordx4 v[176:179], v[150:151], off offset:64
	global_load_dwordx4 v[180:183], v[150:151], off offset:512
	global_load_dwordx4 v[184:187], v[150:151], off offset:576
	v_add_u32_e32 v150, 32, v136
	v_ashrrev_i32_e32 v151, 31, v150
	v_lshlrev_b64 v[150:151], 13, v[150:151]
	v_lshl_add_u64 v[150:151], s[52:53], 0, v[150:151]
	v_add_u32_e32 v152, 16, v136
	v_ashrrev_i32_e32 v153, 31, v152
	v_lshlrev_b64 v[152:153], 13, v[152:153]
	v_lshl_add_u64 v[152:153], s[48:49], 0, v[152:153]
	v_cndmask_b32_e64 v153, v153, v151, s[40:41]
	v_cndmask_b32_e64 v152, v152, v150, s[40:41]
	v_lshl_add_u64 v[150:151], v[150:151], 0, v[134:135]
	v_lshl_add_u64 v[226:227], v[152:153], 0, v[134:135]
	global_load_dwordx4 v[206:209], v[150:151], off
	global_load_dwordx4 v[210:213], v[150:151], off offset:64
	global_load_dwordx4 v[214:217], v[150:151], off offset:512
	global_load_dwordx4 v[218:221], v[150:151], off offset:576
	s_waitcnt vmcnt(8)
	v_pk_add_f32 v[126:127], v[126:127], v[158:159]
	v_pk_add_f32 v[124:125], v[124:125], v[156:157]
	v_pk_add_f32 v[122:123], v[122:123], v[162:163]
	v_pk_add_f32 v[120:121], v[120:121], v[160:161]
	v_pk_add_f32 v[118:119], v[118:119], v[166:167]
	v_pk_add_f32 v[116:117], v[116:117], v[164:165]
	v_pk_add_f32 v[114:115], v[114:115], v[170:171]
	v_pk_add_f32 v[112:113], v[112:113], v[168:169]
	v_add_u32_e32 v188, -16, v136
	v_cmp_gt_u32_e32 vcc, s0, v188
	v_mov_b32_e32 v189, v188
	s_or_b64 s[28:29], s[40:41], vcc
	s_and_saveexec_b64 s[22:23], s[28:29]
	global_store_dwordx4 v[222:223], v[124:127], off nt
	global_store_dwordx4 v[222:223], v[120:123], off offset:64 nt
	global_store_dwordx4 v[222:223], v[116:119], off offset:512 nt
	global_store_dwordx4 v[222:223], v[112:115], off offset:576 nt
	s_or_b64 exec, exec, s[22:23]
	v_add_u32_e32 v150, 48, v136
	v_ashrrev_i32_e32 v151, 31, v150
	v_lshlrev_b64 v[150:151], 13, v[150:151]
	v_lshl_add_u64 v[150:151], s[52:53], 0, v[150:151]
	v_add_u32_e32 v152, 32, v136
	v_ashrrev_i32_e32 v153, 31, v152
	v_lshlrev_b64 v[152:153], 13, v[152:153]
	v_lshl_add_u64 v[152:153], s[48:49], 0, v[152:153]
	v_cndmask_b32_e64 v153, v153, v151, s[40:41]
	v_cndmask_b32_e64 v152, v152, v150, s[40:41]
	v_lshl_add_u64 v[150:151], v[150:151], 0, v[134:135]
	v_lshl_add_u64 v[222:223], v[152:153], 0, v[134:135]
	global_load_dwordx4 v[156:159], v[150:151], off
	global_load_dwordx4 v[160:163], v[150:151], off offset:64
	global_load_dwordx4 v[164:167], v[150:151], off offset:512
	global_load_dwordx4 v[168:171], v[150:151], off offset:576
	s_waitcnt vmcnt(12)
	v_pk_add_f32 v[110:111], v[110:111], v[174:175]
	v_pk_add_f32 v[108:109], v[108:109], v[172:173]
	v_pk_add_f32 v[106:107], v[106:107], v[178:179]
	v_pk_add_f32 v[104:105], v[104:105], v[176:177]
	v_pk_add_f32 v[102:103], v[102:103], v[182:183]
	v_pk_add_f32 v[100:101], v[100:101], v[180:181]
	v_pk_add_f32 v[98:99], v[98:99], v[186:187]
	v_pk_add_f32 v[96:97], v[96:97], v[184:185]
	v_add_u32_e32 v188, 0, v136
	v_cmp_gt_u32_e32 vcc, s0, v188
	v_mov_b32_e32 v189, v188
	s_or_b64 s[28:29], s[40:41], vcc
	s_and_saveexec_b64 s[22:23], s[28:29]
	global_store_dwordx4 v[224:225], v[108:111], off nt
	global_store_dwordx4 v[224:225], v[104:107], off offset:64 nt
	global_store_dwordx4 v[224:225], v[100:103], off offset:512 nt
	global_store_dwordx4 v[224:225], v[96:99], off offset:576 nt
	s_or_b64 exec, exec, s[22:23]
	v_add_u32_e32 v150, 128, v136
	v_ashrrev_i32_e32 v151, 31, v150
	v_lshlrev_b64 v[150:151], 13, v[150:151]
	v_lshl_add_u64 v[150:151], s[52:53], 0, v[150:151]
	v_add_u32_e32 v152, 112, v136
	v_ashrrev_i32_e32 v153, 31, v152
	v_lshlrev_b64 v[152:153], 13, v[152:153]
	v_lshl_add_u64 v[152:153], s[48:49], 0, v[152:153]
	v_cndmask_b32_e64 v153, v153, v151, s[40:41]
	v_cndmask_b32_e64 v152, v152, v150, s[40:41]
	v_lshl_add_u64 v[150:151], v[150:151], 0, v[134:135]
	v_lshl_add_u64 v[224:225], v[152:153], 0, v[134:135]
	global_load_dwordx4 v[172:175], v[150:151], off
	global_load_dwordx4 v[176:179], v[150:151], off offset:64
	global_load_dwordx4 v[180:183], v[150:151], off offset:512
	global_load_dwordx4 v[184:187], v[150:151], off offset:576
	s_waitcnt vmcnt(16)
;     __device__ __forceinline__ void operator()(const f32x4 (&acc)[2][2][4][2], const pg8::Unit& u, int wr, int wc, int fr, int fq) const {
;     ...
; #pragma unroll
;                 for (int bj = 0; bj < 2; ++bj)
; #pragma unroll
;                     for (int n = 0; n < 2; ++n) {
;                         const f32x4 v = *(const f32x4*)(rp + bj * 128 + n * 16) + acc[ai][bj][m][n];
;                         if (wr_ok) __builtin_nontemporal_store(v, (f32x4*)(op + bj * 128 + n * 16));
;                     }
	v_pk_add_f32 v[94:95], v[94:95], v[208:209]
	v_pk_add_f32 v[92:93], v[92:93], v[206:207]
	v_pk_add_f32 v[90:91], v[90:91], v[212:213]
	v_pk_add_f32 v[88:89], v[88:89], v[210:211]
	v_pk_add_f32 v[86:87], v[86:87], v[216:217]
	v_pk_add_f32 v[84:85], v[84:85], v[214:215]
	v_pk_add_f32 v[82:83], v[82:83], v[220:221]
	v_pk_add_f32 v[80:81], v[80:81], v[218:219]
	v_add_u32_e32 v188, 16, v136
	v_cmp_gt_u32_e32 vcc, s0, v188
	v_mov_b32_e32 v189, v188
	s_or_b64 s[28:29], s[40:41], vcc
	s_and_saveexec_b64 s[22:23], s[28:29]
	global_store_dwordx4 v[226:227], v[92:95], off nt
	global_store_dwordx4 v[226:227], v[88:91], off offset:64 nt
	global_store_dwordx4 v[226:227], v[84:87], off offset:512 nt
	global_store_dwordx4 v[226:227], v[80:83], off offset:576 nt
	s_or_b64 exec, exec, s[22:23]
	v_add_u32_e32 v150, 144, v136
	v_ashrrev_i32_e32 v151, 31, v150
	v_lshlrev_b64 v[150:151], 13, v[150:151]
	v_lshl_add_u64 v[150:151], s[52:53], 0, v[150:151]
	v_add_u32_e32 v152, 128, v136
	v_ashrrev_i32_e32 v153, 31, v152
	v_lshlrev_b64 v[152:153], 13, v[152:153]
	v_lshl_add_u64 v[152:153], s[48:49], 0, v[152:153]
	v_cndmask_b32_e64 v153, v153, v151, s[40:41]
	v_cndmask_b32_e64 v152, v152, v150, s[40:41]
	v_lshl_add_u64 v[150:151], v[150:151], 0, v[134:135]
	v_lshl_add_u64 v[226:227], v[152:153], 0, v[134:135]
	global_load_dwordx4 v[206:209], v[150:151], off
	global_load_dwordx4 v[210:213], v[150:151], off offset:64
	global_load_dwordx4 v[214:217], v[150:151], off offset:512
	global_load_dwordx4 v[218:221], v[150:151], off offset:576
	s_waitcnt vmcnt(16)
	v_pk_add_f32 v[78:79], v[78:79], v[158:159]
	v_pk_add_f32 v[76:77], v[76:77], v[156:157]
	v_pk_add_f32 v[74:75], v[74:75], v[162:163]
	v_pk_add_f32 v[72:73], v[72:73], v[160:161]
	v_pk_add_f32 v[70:71], v[70:71], v[166:167]
	v_pk_add_f32 v[68:69], v[68:69], v[164:165]
	v_pk_add_f32 v[66:67], v[66:67], v[170:171]
	v_pk_add_f32 v[64:65], v[64:65], v[168:169]
	v_add_u32_e32 v188, 32, v136
	v_cmp_gt_u32_e32 vcc, s0, v188
	v_mov_b32_e32 v189, v188
	s_or_b64 s[28:29], s[40:41], vcc
	s_and_saveexec_b64 s[22:23], s[28:29]
	global_store_dwordx4 v[222:223], v[76:79], off nt
	global_store_dwordx4 v[222:223], v[72:75], off offset:64 nt
	global_store_dwordx4 v[222:223], v[68:71], off offset:512 nt
	global_store_dwordx4 v[222:223], v[64:67], off offset:576 nt
	s_or_b64 exec, exec, s[22:23]
	v_add_u32_e32 v150, 160, v136
	v_ashrrev_i32_e32 v151, 31, v150
	v_lshlrev_b64 v[150:151], 13, v[150:151]
	v_lshl_add_u64 v[150:151], s[52:53], 0, v[150:151]
	v_add_u32_e32 v152, 144, v136
	v_ashrrev_i32_e32 v153, 31, v152
	v_lshlrev_b64 v[152:153], 13, v[152:153]
	v_lshl_add_u64 v[152:153], s[48:49], 0, v[152:153]
	v_cndmask_b32_e64 v153, v153, v151, s[40:41]
	v_cndmask_b32_e64 v152, v152, v150, s[40:41]
	v_lshl_add_u64 v[150:151], v[150:151], 0, v[134:135]
	v_lshl_add_u64 v[222:223], v[152:153], 0, v[134:135]
	global_load_dwordx4 v[156:159], v[150:151], off
	global_load_dwordx4 v[160:163], v[150:151], off offset:64
	global_load_dwordx4 v[164:167], v[150:151], off offset:512
	global_load_dwordx4 v[168:171], v[150:151], off offset:576
	s_waitcnt vmcnt(16)
;     __device__ __forceinline__ void operator()(const f32x4 (&acc)[2][2][4][2], const pg8::Unit& u, int wr, int wc, int fr, int fq) const {
;     ...
; #pragma unroll
;                 for (int bj = 0; bj < 2; ++bj)
; #pragma unroll
;                     for (int n = 0; n < 2; ++n) {
;                         const f32x4 v = *(const f32x4*)(rp + bj * 128 + n * 16) + acc[ai][bj][m][n];
;                         if (wr_ok) __builtin_nontemporal_store(v, (f32x4*)(op + bj * 128 + n * 16));
;                     }
	v_pk_add_f32 v[62:63], v[62:63], v[174:175]
	v_pk_add_f32 v[60:61], v[60:61], v[172:173]
	v_pk_add_f32 v[58:59], v[58:59], v[178:179]
	v_pk_add_f32 v[56:57], v[56:57], v[176:177]
	v_pk_add_f32 v[54:55], v[54:55], v[182:183]
	v_pk_add_f32 v[52:53], v[52:53], v[180:181]
	v_pk_add_f32 v[50:51], v[50:51], v[186:187]
	v_pk_add_f32 v[48:49], v[48:49], v[184:185]
	v_add_u32_e32 v188, 112, v136
	v_cmp_gt_u32_e32 vcc, s0, v188
	v_mov_b32_e32 v189, v188
	s_or_b64 s[28:29], s[40:41], vcc
	s_and_saveexec_b64 s[22:23], s[28:29]
	global_store_dwordx4 v[224:225], v[60:63], off nt
	global_store_dwordx4 v[224:225], v[56:59], off offset:64 nt
	global_store_dwordx4 v[224:225], v[52:55], off offset:512 nt
	global_store_dwordx4 v[224:225], v[48:51], off offset:576 nt
	s_or_b64 exec, exec, s[22:23]
	v_add_u32_e32 v150, 176, v136
	v_ashrrev_i32_e32 v151, 31, v150
	v_lshlrev_b64 v[150:151], 13, v[150:151]
	v_lshl_add_u64 v[150:151], s[52:53], 0, v[150:151]
	v_add_u32_e32 v152, 160, v136
	v_ashrrev_i32_e32 v153, 31, v152
	v_lshlrev_b64 v[152:153], 13, v[152:153]
	v_lshl_add_u64 v[152:153], s[48:49], 0, v[152:153]
	v_cndmask_b32_e64 v153, v153, v151, s[40:41]
	v_cndmask_b32_e64 v152, v152, v150, s[40:41]
	v_lshl_add_u64 v[150:151], v[150:151], 0, v[134:135]
	v_lshl_add_u64 v[224:225], v[152:153], 0, v[134:135]
	global_load_dwordx4 v[172:175], v[150:151], off
	global_load_dwordx4 v[176:179], v[150:151], off offset:64
	global_load_dwordx4 v[180:183], v[150:151], off offset:512
	global_load_dwordx4 v[184:187], v[150:151], off offset:576
	s_waitcnt vmcnt(16)
	v_pk_add_f32 v[46:47], v[46:47], v[208:209]
	v_pk_add_f32 v[44:45], v[44:45], v[206:207]
	v_pk_add_f32 v[42:43], v[42:43], v[212:213]
	v_pk_add_f32 v[40:41], v[40:41], v[210:211]
	v_pk_add_f32 v[38:39], v[38:39], v[216:217]
	v_pk_add_f32 v[36:37], v[36:37], v[214:215]
	v_pk_add_f32 v[34:35], v[34:35], v[220:221]
	v_pk_add_f32 v[32:33], v[32:33], v[218:219]
	v_add_u32_e32 v188, 128, v136
	v_cmp_gt_u32_e32 vcc, s0, v188
	v_mov_b32_e32 v189, v188
	s_or_b64 s[28:29], s[40:41], vcc
	s_and_saveexec_b64 s[22:23], s[28:29]
	global_store_dwordx4 v[226:227], v[44:47], off nt
	global_store_dwordx4 v[226:227], v[40:43], off offset:64 nt
	global_store_dwordx4 v[226:227], v[36:39], off offset:512 nt
	global_store_dwordx4 v[226:227], v[32:35], off offset:576 nt
	s_or_b64 exec, exec, s[22:23]
	s_waitcnt vmcnt(12)
	v_pk_add_f32 v[30:31], v[30:31], v[158:159]
	v_pk_add_f32 v[28:29], v[28:29], v[156:157]
	v_pk_add_f32 v[26:27], v[26:27], v[162:163]
	v_pk_add_f32 v[24:25], v[24:25], v[160:161]
	v_pk_add_f32 v[22:23], v[22:23], v[166:167]
	v_pk_add_f32 v[20:21], v[20:21], v[164:165]
	v_pk_add_f32 v[18:19], v[18:19], v[170:171]
	v_pk_add_f32 v[16:17], v[16:17], v[168:169]
	v_add_u32_e32 v188, 144, v136
	v_cmp_gt_u32_e32 vcc, s0, v188
	v_mov_b32_e32 v189, v188
	s_or_b64 s[28:29], s[40:41], vcc
	s_and_saveexec_b64 s[22:23], s[28:29]
	global_store_dwordx4 v[222:223], v[28:31], off nt
	global_store_dwordx4 v[222:223], v[24:27], off offset:64 nt
	global_store_dwordx4 v[222:223], v[20:23], off offset:512 nt
	global_store_dwordx4 v[222:223], v[16:19], off offset:576 nt
	s_or_b64 exec, exec, s[22:23]
	s_waitcnt vmcnt(8)
	v_pk_add_f32 v[14:15], v[14:15], v[174:175]
	v_pk_add_f32 v[12:13], v[12:13], v[172:173]
	v_pk_add_f32 v[10:11], v[10:11], v[178:179]
	v_pk_add_f32 v[8:9], v[8:9], v[176:177]
	v_pk_add_f32 v[6:7], v[6:7], v[182:183]
	v_pk_add_f32 v[4:5], v[4:5], v[180:181]
	v_pk_add_f32 v[2:3], v[2:3], v[186:187]
	v_pk_add_f32 v[0:1], v[0:1], v[184:185]
	v_add_u32_e32 v188, 160, v136
	v_cmp_gt_u32_e32 vcc, s0, v188
	v_mov_b32_e32 v189, v188
	s_or_b64 s[28:29], s[40:41], vcc
	s_and_saveexec_b64 s[22:23], s[28:29]
	global_store_dwordx4 v[224:225], v[12:15], off nt
	global_store_dwordx4 v[224:225], v[8:11], off offset:64 nt
	global_store_dwordx4 v[224:225], v[4:7], off offset:512 nt
	global_store_dwordx4 v[224:225], v[0:3], off offset:576 nt
	s_or_b64 exec, exec, s[22:23]
	s_mov_b64 s[0:1], 0x160000
	s_mov_b64 s[22:23], 0

; #define LAS __attribute__((address_space(3)))
; __device__ __forceinline__ unsigned pk2(float lo, float hi) { return pg8::cvt_pk_bf16(lo, hi); }
; template <int NCH, class RB, class EP>
; __device__ __forceinline__ void tail_gemm(const bf16* A16, const bf16* Bt, int K, int ngroups, int vcu, int G, LAS unsigned char* lds, int wave, RB rb, EP ep) {
;     ...
;         for (int k = 0; k < kw; k += 32) {
;             const bf16x8 av = *(const bf16x8*)(ap + k);
; #pragma unroll
;             for (int c = 0; c < NCH; ++c) { const bf16x8 bv = *(const bf16x8*)(Bt + (size_t)(rb(g, c) + r) * K + wave * kw + 8 * q + k);
;                 acc[c] = __builtin_amdgcn_mfma_f32_16x16x32_bf16(av, bv, acc[c], 0, 0, 0); }
;         }
; #pragma unroll
;         for (int c = 0; c < NCH; ++c) *(LAS f32x4*)(red + (wave * NCH + c) * 256 + lane * 4) = acc[c];
;         __syncthreads();
;         if (tid < 256) {
;             float v[NCH];
; #pragma unroll
;             for (int c = 0; c < NCH; ++c) { float s = 0.f;
; #pragma unroll
;                 for (int w = 0; w < 8; ++w) s += red[(w * NCH + c) * 256 + tid];
;                 v[c] = s; }
;             ep(g, 4 * (tid >> 6) + (tid & 3), (tid >> 2) & 15, v);
;         }
;         __syncthreads();
;     }
; }
; __global__ void __launch_bounds__(NTHR, 2) mk_fwd(Args a_byval) {
;     ...
;                   tail_gemm<2>((const bf16*)(ws + WS_HN) + (size_t)8192 * DM, (const bf16*)(wl + OFF_WGU), DM, DFF / 16, vcu, G, lds, wave0,
;                       [](int g, int ch) { return (g >> 3) * 256 + (g & 7) * 16 + ch * 128; },
;                       [=](int g, int r, int c, const float* v) { const float sg = __builtin_amdgcn_rcpf(1.f + __builtin_amdgcn_exp2f(-v[0] * 1.4426950408889634f));
;                           ACT[(size_t)(8192 + r) * DFF + g * 16 + c] = (bf16)(pk2(v[0] * sg * v[1], 0.f) & 0xffffu); }); }
.LBB0_93:
	v_lshl_add_u64 v[24:25], v[18:19], 0, s[30:31]
	v_add_co_u32_e32 v32, vcc, 0x1d800000, v24
	v_lshl_add_u64 v[28:29], v[14:15], 0, s[30:31]
	s_nop 0
	v_addc_co_u32_e32 v33, vcc, 0, v25, vcc
	v_add_co_u32_e32 v34, vcc, 0x1a80000, v28
	v_lshl_add_u64 v[24:25], v[16:17], 0, s[30:31]
	s_nop 0
	v_addc_co_u32_e32 v35, vcc, 0, v29, vcc
	v_add_co_u32_e32 v36, vcc, 0x1a80000, v24
	s_nop 1
	v_addc_co_u32_e32 v37, vcc, 0, v25, vcc
	global_load_dwordx4 v[64:67], v[32:33], off
	global_load_dwordx4 v[68:71], v[34:35], off
	global_load_dwordx4 v[72:75], v[36:37], off
	global_load_dwordx4 v[76:79], v[32:33], off offset:64
	global_load_dwordx4 v[80:83], v[34:35], off offset:64
	global_load_dwordx4 v[84:87], v[36:37], off offset:64
	global_load_dwordx4 v[88:91], v[32:33], off offset:128
	global_load_dwordx4 v[92:95], v[34:35], off offset:128
	global_load_dwordx4 v[96:99], v[36:37], off offset:128
	global_load_dwordx4 v[100:103], v[32:33], off offset:192
	global_load_dwordx4 v[104:107], v[34:35], off offset:192
	global_load_dwordx4 v[108:111], v[36:37], off offset:192
	global_load_dwordx4 v[112:115], v[32:33], off offset:256
	global_load_dwordx4 v[116:119], v[34:35], off offset:256
	global_load_dwordx4 v[120:123], v[36:37], off offset:256
	global_load_dwordx4 v[124:127], v[32:33], off offset:320
	global_load_dwordx4 v[156:159], v[34:35], off offset:320
	global_load_dwordx4 v[160:163], v[36:37], off offset:320
	global_load_dwordx4 v[164:167], v[32:33], off offset:384
	global_load_dwordx4 v[168:171], v[34:35], off offset:384
	global_load_dwordx4 v[172:175], v[36:37], off offset:384
	global_load_dwordx4 v[176:179], v[32:33], off offset:448
	global_load_dwordx4 v[180:183], v[34:35], off offset:448
	global_load_dwordx4 v[184:187], v[36:37], off offset:448
	s_waitcnt vmcnt(21)
	v_mfma_f32_16x16x32_bf16 v[4:7], v[64:67], v[68:71], v[4:7]
	v_mfma_f32_16x16x32_bf16 v[0:3], v[64:67], v[72:75], v[0:3]
	s_waitcnt vmcnt(18)
	v_mfma_f32_16x16x32_bf16 v[4:7], v[76:79], v[80:83], v[4:7]
	v_mfma_f32_16x16x32_bf16 v[0:3], v[76:79], v[84:87], v[0:3]
	s_waitcnt vmcnt(15)
	v_mfma_f32_16x16x32_bf16 v[4:7], v[88:91], v[92:95], v[4:7]
	v_mfma_f32_16x16x32_bf16 v[0:3], v[88:91], v[96:99], v[0:3]
	s_waitcnt vmcnt(12)
	v_mfma_f32_16x16x32_bf16 v[4:7], v[100:103], v[104:107], v[4:7]
	v_mfma_f32_16x16x32_bf16 v[0:3], v[100:103], v[108:111], v[0:3]
	s_waitcnt vmcnt(9)
	v_mfma_f32_16x16x32_bf16 v[4:7], v[112:115], v[116:119], v[4:7]
	v_mfma_f32_16x16x32_bf16 v[0:3], v[112:115], v[120:123], v[0:3]
	s_waitcnt vmcnt(6)
	v_mfma_f32_16x16x32_bf16 v[4:7], v[124:127], v[156:159], v[4:7]
	v_mfma_f32_16x16x32_bf16 v[0:3], v[124:127], v[160:163], v[0:3]
	s_waitcnt vmcnt(3)
	v_mfma_f32_16x16x32_bf16 v[4:7], v[164:167], v[168:171], v[4:7]
	v_mfma_f32_16x16x32_bf16 v[0:3], v[164:167], v[172:175], v[0:3]
	s_waitcnt vmcnt(0)
	v_mfma_f32_16x16x32_bf16 v[4:7], v[176:179], v[180:183], v[4:7]
	v_mfma_f32_16x16x32_bf16 v[0:3], v[176:179], v[184:187], v[0:3]
	s_nop 3
	s_nop 3
	ds_write_b128 v21, v[4:7]
	s_nop 1
	ds_write_b128 v21, v[0:3] offset:1024
	s_waitcnt lgkmcnt(0)
	s_barrier
	s_and_saveexec_b64 s[22:23], s[40:41]
	s_cbranch_execz .LBB0_91
	ds_read2st64_b32 v[0:1], v22 offset1:4
	ds_read2st64_b32 v[2:3], v22 offset0:8 offset1:12
	ds_read2st64_b32 v[4:5], v22 offset0:16 offset1:20
	ds_read2st64_b32 v[6:7], v22 offset0:24 offset1:28
	ds_read2st64_b32 v[14:15], v22 offset0:32 offset1:36
	ds_read2st64_b32 v[16:17], v22 offset0:40 offset1:44
	ds_read2st64_b32 v[18:19], v22 offset0:48 offset1:52
	ds_read2st64_b32 v[24:25], v22 offset0:56 offset1:60
	s_waitcnt lgkmcnt(7)
	v_pk_add_f32 v[0:1], v[0:1], 0 op_sel_hi:[1,0]
	s_lshl_b32 s20, s18, 4
	s_waitcnt lgkmcnt(6)
	v_pk_add_f32 v[0:1], v[0:1], v[2:3]
	s_ashr_i32 s21, s20, 31
	s_waitcnt lgkmcnt(5)
	v_pk_add_f32 v[0:1], v[0:1], v[4:5]
	s_waitcnt lgkmcnt(4)
	v_pk_add_f32 v[0:1], v[0:1], v[6:7]
	s_waitcnt lgkmcnt(3)
	v_pk_add_f32 v[0:1], v[0:1], v[14:15]
	s_waitcnt lgkmcnt(2)
	v_pk_add_f32 v[0:1], v[0:1], v[16:17]
	s_waitcnt lgkmcnt(1)
	v_pk_add_f32 v[0:1], v[0:1], v[18:19]
	s_waitcnt lgkmcnt(0)
	v_pk_add_f32 v[0:1], v[0:1], v[24:25]
	s_nop 0
	v_mul_f32_e32 v2, 0xbfb8aa3b, v0
	v_exp_f32_e32 v2, v2
	s_nop 0
	v_add_f32_e32 v2, 1.0, v2
	v_rcp_f32_e32 v2, v2
	s_nop 0
	v_mul_f32_e32 v0, v0, v2
	v_mul_f32_e32 v0, v0, v1
	v_cvt_pk_bf16_f32 v2, v0, v149
	v_lshl_add_u64 v[0:1], s[20:21], 1, v[8:9]
	global_store_short v[0:1], v2, off
	s_branch .LBB0_91

; __device__ __forceinline__ int opaque_tid(int wave_s) { int l; asm volatile("v_mbcnt_lo_u32_b32 %0, -1, 0\n\tv_mbcnt_hi_u32_b32 %0, -1, %0" : "=v"(l)); return (wave_s << 6) | l; }
; __device__ __forceinline__ void norm_row(const float* src, const float* g, bf16* dst, float* hdst, int lane) {
;     f32x4 v[8]; float ss = 0.f;
; #pragma unroll
;     for (int j = 0; j < 8; ++j) { v[j] = src ? *(const f32x4*)(src + 4 * lane + 256 * j) : (f32x4){0.f, 0.f, 0.f, 0.f}; ss += v[j].x * v[j].x + v[j].y * v[j].y + v[j].z * v[j].z + v[j].w * v[j].w; }
;     ss = wave_sum(ss);
;     const float rstd = rsqrtf(ss * (1.0f / DM) + EPS);
; #pragma unroll
;     for (int j = 0; j < 8; ++j) {
;         const f32x4 gg = *(const f32x4*)(g + 4 * lane + 256 * j);
; __device__ __forceinline__ void phase_norm(KA a, const float* g, int vcu, int G, int wave) {
;     const int lane = opaque_tid(wave) & 63;
;     const int gw = vcu * NWAVES + wave, NGW = G * NWAVES;
;     for (int t = gw; t < T_; t += NGW) norm_row((const float*)(a->ws + WS_H) + (size_t)t * DM, g, (bf16*)(a->ws + WS_HN) + (size_t)t * DM, nullptr, lane);
; }
.LBB0_97:
	s_lshl_b32 s5, s81, 8
	s_add_i32 s5, s5, s11
	s_sub_i32 s5, s5, s81
	s_add_i32 s40, s5, s81
	s_cmpk_lt_i32 s40, 0x2010
	v_mbcnt_lo_u32_b32 v0, -1, 0
	v_mbcnt_hi_u32_b32 v0, -1, v0
	s_cbranch_scc0 .LBB0_100
	v_and_b32_e32 v1, 64, v196
	v_add_u32_e32 v1, 64, v1
	v_xor_b32_e32 v2, 1, v196
	v_cmp_lt_i32_e32 vcc, v2, v1
	s_load_dwordx2 s[18:19], s[36:37], 0xb8
	v_readlane_b32 s1, v254, 62
	v_cndmask_b32_e32 v2, v196, v2, vcc
	v_lshlrev_b32_e32 v48, 2, v2
	v_xor_b32_e32 v2, 2, v196
	v_cmp_lt_i32_e32 vcc, v2, v1
	s_lshl_b32 s20, s1, 11
	s_ashr_i32 s21, s20, 31
	v_cndmask_b32_e32 v2, v196, v2, vcc
	v_lshlrev_b32_e32 v49, 2, v2
	v_xor_b32_e32 v2, 4, v196
	v_cmp_lt_i32_e32 vcc, v2, v1
	s_lshl_b32 s42, s15, 3
	s_lshl_b64 s[20:21], s[20:21], 2
	v_cndmask_b32_e32 v2, v196, v2, vcc
	v_lshlrev_b32_e32 v50, 2, v2
	v_xor_b32_e32 v2, 8, v196
	v_cmp_lt_i32_e32 vcc, v2, v1
	s_waitcnt lgkmcnt(0)
	s_add_u32 s18, s18, s20
	s_addc_u32 s19, s19, s21
	v_cndmask_b32_e32 v2, v196, v2, vcc
	v_lshlrev_b32_e32 v51, 2, v2
	v_xor_b32_e32 v2, 16, v196
	v_cmp_lt_i32_e32 vcc, v2, v1
	s_ashr_i32 s41, s40, 31
	s_ashr_i32 s43, s42, 31
	v_cndmask_b32_e32 v2, v196, v2, vcc
	v_lshlrev_b32_e32 v52, 2, v2
	v_xor_b32_e32 v2, 32, v196
	v_cmp_lt_i32_e32 vcc, v2, v1
	s_lshl_b64 s[44:45], s[42:43], 12
	s_lshl_b64 s[48:49], s[42:43], 13
	v_cndmask_b32_e32 v1, v196, v2, vcc
	v_lshlrev_b32_e32 v53, 2, v1
	v_lshlrev_b32_e32 v1, 4, v0
	v_and_b32_e32 v148, 0x3f0, v1
	v_lshl_add_u64 v[32:33], s[18:19], 0, v[148:149]
	s_mov_b64 s[18:19], 0x1000
	v_lshl_add_u64 v[34:35], v[32:33], 0, s[18:19]
	s_mov_b64 s[18:19], 0x1400
	v_lshl_add_u64 v[36:37], v[32:33], 0, s[18:19]
	s_mov_b64 s[18:19], 0x1800
	v_lshl_add_u64 v[38:39], v[32:33], 0, s[18:19]
	s_mov_b64 s[18:19], 0x1c00
	v_lshl_add_u64 v[40:41], v[32:33], 0, s[18:19]
	s_lshl_b64 s[18:19], s[40:41], 12
	v_and_b32_e32 v0, 63, v0
	v_lshl_or_b32 v42, v0, 3, s18
	v_mov_b32_e32 v43, s19
	s_lshl_b64 s[18:19], s[40:41], 13
	v_lshl_or_b32 v44, v0, 4, s18
	v_mov_b32_e32 v45, s19
	global_load_dwordx4 v[64:67], v[32:33], off
	global_load_dwordx4 v[68:71], v[32:33], off offset:1024
	global_load_dwordx4 v[72:75], v[32:33], off offset:2048
	global_load_dwordx4 v[76:79], v[32:33], off offset:3072
	global_load_dwordx4 v[80:83], v[34:35], off
	global_load_dwordx4 v[84:87], v[36:37], off
	global_load_dwordx4 v[88:91], v[38:39], off
	global_load_dwordx4 v[92:95], v[40:41], off
; __device__ __forceinline__ int opaque_tid(int wave_s) { int l; asm volatile("v_mbcnt_lo_u32_b32 %0, -1, 0\n\tv_mbcnt_hi_u32_b32 %0, -1, %0" : "=v"(l)); return (wave_s << 6) | l; }
; __device__ __forceinline__ unsigned pk2(float lo, float hi) { return pg8::cvt_pk_bf16(lo, hi); }
; __device__ __forceinline__ void norm_row(const float* src, const float* g, bf16* dst, float* hdst, int lane) {
;     f32x4 v[8]; float ss = 0.f;
; #pragma unroll
;     for (int j = 0; j < 8; ++j) { v[j] = src ? *(const f32x4*)(src + 4 * lane + 256 * j) : (f32x4){0.f, 0.f, 0.f, 0.f}; ss += v[j].x * v[j].x + v[j].y * v[j].y + v[j].z * v[j].z + v[j].w * v[j].w; }
;     ss = wave_sum(ss);
;     const float rstd = rsqrtf(ss * (1.0f / DM) + EPS);
; #pragma unroll
;     for (int j = 0; j < 8; ++j) {
;         const f32x4 gg = *(const f32x4*)(g + 4 * lane + 256 * j);
;         u32x2 w; w.x = pk2(v[j].x * rstd * gg.x, v[j].y * rstd * gg.y); w.y = pk2(v[j].z * rstd * gg.z, v[j].w * rstd * gg.w);
;         *(u32x2*)(dst + 4 * lane + 256 * j) = w;
;         if (hdst) *(f32x4*)(hdst + 4 * lane + 256 * j) = v[j];
;     }
; }
; __device__ __forceinline__ void phase_norm(KA a, const float* g, int vcu, int G, int wave) {
;     const int lane = opaque_tid(wave) & 63;
;     const int gw = vcu * NWAVES + wave, NGW = G * NWAVES;
;     for (int t = gw; t < T_; t += NGW) norm_row((const float*)(a->ws + WS_H) + (size_t)t * DM, g, (bf16*)(a->ws + WS_HN) + (size_t)t * DM, nullptr, lane);
; }
.LBB0_99:
	v_lshl_add_u64 v[0:1], s[16:17], 0, v[44:45]
	v_add_co_u32_e32 v2, vcc, 0x17600000, v0
	v_lshl_add_u64 v[60:61], s[16:17], 0, v[42:43]
	s_nop 0
	v_addc_co_u32_e32 v3, vcc, 0, v1, vcc
	global_load_dwordx4 v[28:31], v[2:3], off
	global_load_dwordx4 v[24:27], v[2:3], off offset:1024
	global_load_dwordx4 v[20:23], v[2:3], off offset:2048
	global_load_dwordx4 v[16:19], v[2:3], off offset:3072
	v_add_co_u32_e32 v0, vcc, s26, v0
	s_add_i32 s40, s40, s42
	s_nop 0
	v_addc_co_u32_e32 v1, vcc, 0, v1, vcc
	global_load_dwordx4 v[12:15], v[0:1], off
	global_load_dwordx4 v[8:11], v[0:1], off offset:1024
	global_load_dwordx4 v[96:99], v[0:1], off offset:2048
	global_load_dwordx4 v[100:103], v[0:1], off offset:3072
	v_lshl_add_u64 v[42:43], v[42:43], 0, s[44:45]
	v_lshl_add_u64 v[44:45], v[44:45], 0, s[48:49]
	s_cmpk_gt_i32 s40, 0x200f
	s_waitcnt vmcnt(0)
	v_mul_f32_e32 v4, v29, v29
	v_mul_f32_e32 v5, v25, v25
	v_fmac_f32_e32 v4, v28, v28
	v_fmac_f32_e32 v5, v24, v24
	v_fmac_f32_e32 v4, v30, v30
	v_fmac_f32_e32 v5, v26, v26
	v_fmac_f32_e32 v4, v31, v31
	v_fmac_f32_e32 v5, v27, v27
	v_add_f32_e32 v4, v4, v5
	v_mul_f32_e32 v5, v21, v21
	v_fmac_f32_e32 v5, v20, v20
	v_mul_f32_e32 v2, v17, v17
	v_fmac_f32_e32 v5, v22, v22
	v_fmac_f32_e32 v2, v16, v16
	v_fmac_f32_e32 v5, v23, v23
	v_fmac_f32_e32 v2, v18, v18
	v_add_f32_e32 v4, v4, v5
	v_fmac_f32_e32 v2, v19, v19
	v_add_f32_e32 v6, v4, v2
	v_mov_b32_e32 v4, v13
	v_mov_b32_e32 v5, v9
	v_mov_b32_e32 v2, v12
	v_mov_b32_e32 v3, v8
	v_pk_mul_f32 v[4:5], v[4:5], v[4:5]
	s_nop 0
	v_pk_fma_f32 v[2:3], v[2:3], v[2:3], v[4:5]
	v_mov_b32_e32 v4, v14
	v_mov_b32_e32 v5, v10
	v_pk_fma_f32 v[2:3], v[4:5], v[4:5], v[2:3]
	v_mov_b32_e32 v4, v15
	v_mov_b32_e32 v5, v11
	v_pk_fma_f32 v[2:3], v[4:5], v[4:5], v[2:3]
	s_nop 0
	v_add_f32_e32 v2, v6, v2
	v_add_f32_e32 v56, v2, v3
	v_mov_b32_e32 v4, v96
	v_mov_b32_e32 v5, v97
	v_mov_b32_e32 v6, v98
	v_mov_b32_e32 v7, v99
	s_nop 0
	v_mov_b32_e32 v0, v100
	v_mov_b32_e32 v1, v101
	v_mov_b32_e32 v2, v102
	v_mov_b32_e32 v3, v103
	v_mov_b32_e32 v54, v5
	v_mov_b32_e32 v55, v1
	v_mov_b32_e32 v46, v4
	v_mov_b32_e32 v47, v0
	v_pk_mul_f32 v[54:55], v[54:55], v[54:55]
	s_nop 0
	v_pk_fma_f32 v[46:47], v[46:47], v[46:47], v[54:55]
	v_mov_b32_e32 v54, v6
	v_mov_b32_e32 v55, v2
	v_pk_fma_f32 v[46:47], v[54:55], v[54:55], v[46:47]
	v_mov_b32_e32 v54, v7
	v_mov_b32_e32 v55, v3
	v_pk_fma_f32 v[46:47], v[54:55], v[54:55], v[46:47]
	s_nop 0
	v_add_f32_e32 v46, v56, v46
	v_add_f32_e32 v46, v46, v47
	ds_bpermute_b32 v47, v48, v46
	s_waitcnt lgkmcnt(0)
	v_add_f32_e32 v46, v46, v47
	ds_bpermute_b32 v47, v49, v46
	s_waitcnt lgkmcnt(0)
	v_add_f32_e32 v46, v46, v47
	ds_bpermute_b32 v47, v50, v46
	s_waitcnt lgkmcnt(0)
	v_add_f32_e32 v46, v46, v47
	ds_bpermute_b32 v47, v51, v46
	s_waitcnt lgkmcnt(0)
	v_add_f32_e32 v46, v46, v47
	ds_bpermute_b32 v47, v52, v46
	s_waitcnt lgkmcnt(0)
	v_add_f32_e32 v46, v46, v47
	ds_bpermute_b32 v47, v53, v46
	s_waitcnt lgkmcnt(0)
	v_add_f32_e32 v46, v46, v47
	v_fmamk_f32 v46, v46, 0x3a000000, v154
	v_cmp_gt_f32_e32 vcc, s54, v46
	v_mul_f32_e32 v47, 0x4b800000, v46
	s_nop 0
	v_cndmask_b32_e32 v46, v46, v47, vcc
	v_rsq_f32_e32 v46, v46
	s_nop 0
	v_mul_f32_e32 v47, 0x45800000, v46
	v_cndmask_b32_e32 v54, v46, v47, vcc
	v_mul_f32_e32 v28, v28, v54
	v_mul_f32_e32 v29, v29, v54
	v_mul_f32_e32 v24, v24, v54
	v_mul_f32_e32 v25, v25, v54
	v_mul_f32_e32 v20, v20, v54
	v_mul_f32_e32 v21, v21, v54
	v_mul_f32_e32 v16, v16, v54
	v_mul_f32_e32 v17, v17, v54
	v_mul_f32_e32 v12, v12, v54
	v_mul_f32_e32 v13, v13, v54
	v_mul_f32_e32 v8, v8, v54
	v_mul_f32_e32 v9, v9, v54
	v_mul_f32_e32 v4, v4, v54
	v_mul_f32_e32 v5, v5, v54
	v_mul_f32_e32 v0, v0, v54
	v_mul_f32_e32 v1, v1, v54
	v_mul_f32_e32 v28, v64, v28
	v_mul_f32_e32 v29, v65, v29
	v_cvt_pk_bf16_f32 v46, v28, v29
	v_mul_f32_e32 v28, v30, v54
	v_mul_f32_e32 v28, v66, v28
	v_mul_f32_e32 v29, v31, v54
	v_mul_f32_e32 v29, v67, v29
	v_cvt_pk_bf16_f32 v47, v28, v29
	v_add_co_u32_e32 v28, vcc, s0, v60
	s_nop 1
	v_addc_co_u32_e32 v29, vcc, 0, v61, vcc
	global_store_dwordx2 v[28:29], v[46:47], off
	v_mul_f32_e32 v24, v68, v24
	v_mul_f32_e32 v25, v69, v25
	v_cvt_pk_bf16_f32 v24, v24, v25
	v_mul_f32_e32 v25, v26, v54
	v_mul_f32_e32 v25, v70, v25
	v_mul_f32_e32 v26, v27, v54
	v_mul_f32_e32 v26, v71, v26
	v_cvt_pk_bf16_f32 v25, v25, v26
	global_store_dwordx2 v[28:29], v[24:25], off offset:512
	v_mul_f32_e32 v20, v72, v20
	v_mul_f32_e32 v21, v73, v21
	v_cvt_pk_bf16_f32 v20, v20, v21
	v_mul_f32_e32 v21, v22, v54
	v_mul_f32_e32 v21, v74, v21
	v_mul_f32_e32 v22, v23, v54
	v_mul_f32_e32 v22, v75, v22
	v_cvt_pk_bf16_f32 v21, v21, v22
	global_store_dwordx2 v[28:29], v[20:21], off offset:1024
	v_mul_f32_e32 v16, v16, v76
	v_mul_f32_e32 v17, v17, v77
	v_cvt_pk_bf16_f32 v16, v16, v17
	v_mul_f32_e32 v17, v18, v54
	v_mul_f32_e32 v17, v17, v78
	v_mul_f32_e32 v18, v19, v54
	v_mul_f32_e32 v18, v18, v79
	v_cvt_pk_bf16_f32 v17, v17, v18
	global_store_dwordx2 v[28:29], v[16:17], off offset:1536
	v_mul_f32_e32 v12, v12, v80
	v_mul_f32_e32 v13, v13, v81
	v_cvt_pk_bf16_f32 v12, v12, v13
	v_mul_f32_e32 v13, v14, v54
	v_mul_f32_e32 v13, v13, v82
	v_mul_f32_e32 v14, v15, v54
	v_mul_f32_e32 v14, v14, v83
	v_cvt_pk_bf16_f32 v13, v13, v14
	global_store_dwordx2 v[28:29], v[12:13], off offset:2048
	v_mul_f32_e32 v8, v8, v84
	v_mul_f32_e32 v9, v9, v85
	v_cvt_pk_bf16_f32 v8, v8, v9
	v_mul_f32_e32 v9, v10, v54
	v_mul_f32_e32 v9, v9, v86
	v_mul_f32_e32 v10, v11, v54
	v_mul_f32_e32 v10, v10, v87
	v_cvt_pk_bf16_f32 v9, v9, v10
	global_store_dwordx2 v[28:29], v[8:9], off offset:2560
	v_mul_f32_e32 v4, v4, v88
	v_mul_f32_e32 v5, v5, v89
	v_cvt_pk_bf16_f32 v4, v4, v5
	v_mul_f32_e32 v5, v6, v54
	v_mul_f32_e32 v5, v5, v90
	v_mul_f32_e32 v6, v7, v54
	v_mul_f32_e32 v6, v6, v91
	v_cvt_pk_bf16_f32 v5, v5, v6
	global_store_dwordx2 v[28:29], v[4:5], off offset:3072
	v_mul_f32_e32 v0, v0, v92
	v_mul_f32_e32 v1, v1, v93
	v_cvt_pk_bf16_f32 v0, v0, v1
	v_mul_f32_e32 v1, v2, v54
	v_mul_f32_e32 v1, v1, v94
	v_mul_f32_e32 v2, v3, v54
	v_mul_f32_e32 v2, v2, v95
	v_cvt_pk_bf16_f32 v1, v1, v2
	global_store_dwordx2 v[28:29], v[0:1], off offset:3584
	s_cbranch_scc0 .LBB0_99

;     __device__ __forceinline__ void operator()(const f32x4 (&acc)[2][2][4][2], const pg8::Unit& u, int wr, int wc, int fr, int fq) const {
;         const int row0 = u.pm * 256 + wr * 64 + fr, col0 = u.pn * 256 + wc * 32 + 4 * fq;
; #pragma unroll
;         for (int ai = 0; ai < 2; ++ai)
; #pragma unroll
;             for (int m = 0; m < 4; ++m) {
;                 const int row = row0 + ai * 128 + m * 16;
;                 float* rp = H + (size_t)row * DM + col0;
;                 float* op = OUT ? (OUT + (size_t)(row - NMETA) * DM + col0) : rp;
;                 const bool wr_ok = OUT ? (row >= NMETA && row < T_) : true;
; #pragma unroll
;                 for (int bj = 0; bj < 2; ++bj)
; #pragma unroll
;                     for (int n = 0; n < 2; ++n) {
;                         const f32x4 v = *(const f32x4*)(rp + bj * 128 + n * 16) + acc[ai][bj][m][n];
;                         if (wr_ok) __builtin_nontemporal_store(v, (f32x4*)(op + bj * 128 + n * 16));
;                     }
;             }
;     }
.LBB0_118:
	v_lshl_add_u32 v144, s60, 8, v136
	v_lshl_or_b32 v134, s38, 8, v138
	v_ashrrev_i32_e32 v135, 31, v134
	v_lshlrev_b64 v[146:147], 2, v[134:135]
	s_mov_b32 s3, 0x100000
	s_mov_b64 s[22:23], 0x100000
	s_mov_b64 s[0:1], 0x160000
	v_readlane_b32 s36, v255, 5
	v_readlane_b32 s37, v255, 6
	v_readlane_b32 s66, v255, 8
	v_mov_b32_e32 v150, v144
	v_ashrrev_i32_e32 v151, 31, v150
	v_lshlrev_b64 v[150:151], 13, v[150:151]
	v_lshl_add_u64 v[150:151], s[42:43], 0, v[150:151]
	v_lshl_add_u64 v[150:151], v[150:151], 0, v[146:147]
	v_mov_b32_e32 v222, v150
	v_mov_b32_e32 v223, v151
	global_load_dwordx4 v[156:159], v[150:151], off
	global_load_dwordx4 v[160:163], v[150:151], off offset:64
	global_load_dwordx4 v[164:167], v[150:151], off offset:512
	global_load_dwordx4 v[168:171], v[150:151], off offset:576
	v_add_u32_e32 v150, 16, v144
	v_ashrrev_i32_e32 v151, 31, v150
	v_lshlrev_b64 v[150:151], 13, v[150:151]
	v_lshl_add_u64 v[150:151], s[42:43], 0, v[150:151]
	v_lshl_add_u64 v[150:151], v[150:151], 0, v[146:147]
	v_mov_b32_e32 v224, v150
	v_mov_b32_e32 v225, v151
	global_load_dwordx4 v[172:175], v[150:151], off
	global_load_dwordx4 v[176:179], v[150:151], off offset:64
	global_load_dwordx4 v[180:183], v[150:151], off offset:512
	global_load_dwordx4 v[184:187], v[150:151], off offset:576
	v_add_u32_e32 v150, 32, v144
	v_ashrrev_i32_e32 v151, 31, v150
	v_lshlrev_b64 v[150:151], 13, v[150:151]
	v_lshl_add_u64 v[150:151], s[42:43], 0, v[150:151]
	v_lshl_add_u64 v[150:151], v[150:151], 0, v[146:147]
	v_mov_b32_e32 v226, v150
	v_mov_b32_e32 v227, v151
	global_load_dwordx4 v[206:209], v[150:151], off
	global_load_dwordx4 v[210:213], v[150:151], off offset:64
	global_load_dwordx4 v[214:217], v[150:151], off offset:512
	global_load_dwordx4 v[218:221], v[150:151], off offset:576
	s_waitcnt vmcnt(8)
	v_pk_add_f32 v[126:127], v[126:127], v[158:159]
	v_pk_add_f32 v[124:125], v[124:125], v[156:157]
	v_pk_add_f32 v[122:123], v[122:123], v[162:163]
	v_pk_add_f32 v[120:121], v[120:121], v[160:161]
	v_pk_add_f32 v[118:119], v[118:119], v[166:167]
	v_pk_add_f32 v[116:117], v[116:117], v[164:165]
	v_pk_add_f32 v[114:115], v[114:115], v[170:171]
	v_pk_add_f32 v[112:113], v[112:113], v[168:169]
	global_store_dwordx4 v[222:223], v[124:127], off nt
	global_store_dwordx4 v[222:223], v[120:123], off offset:64 nt
	global_store_dwordx4 v[222:223], v[116:119], off offset:512 nt
	global_store_dwordx4 v[222:223], v[112:115], off offset:576 nt
	v_add_u32_e32 v150, 48, v144
	v_ashrrev_i32_e32 v151, 31, v150
	v_lshlrev_b64 v[150:151], 13, v[150:151]
	v_lshl_add_u64 v[150:151], s[42:43], 0, v[150:151]
	v_lshl_add_u64 v[150:151], v[150:151], 0, v[146:147]
	v_mov_b32_e32 v222, v150
	v_mov_b32_e32 v223, v151
	global_load_dwordx4 v[156:159], v[150:151], off
	global_load_dwordx4 v[160:163], v[150:151], off offset:64
	global_load_dwordx4 v[164:167], v[150:151], off offset:512
	global_load_dwordx4 v[168:171], v[150:151], off offset:576
	s_waitcnt vmcnt(12)
	v_pk_add_f32 v[110:111], v[110:111], v[174:175]
	v_pk_add_f32 v[108:109], v[108:109], v[172:173]
	v_pk_add_f32 v[106:107], v[106:107], v[178:179]
	v_pk_add_f32 v[104:105], v[104:105], v[176:177]
	v_pk_add_f32 v[102:103], v[102:103], v[182:183]
	v_pk_add_f32 v[100:101], v[100:101], v[180:181]
	v_pk_add_f32 v[98:99], v[98:99], v[186:187]
	v_pk_add_f32 v[96:97], v[96:97], v[184:185]
	global_store_dwordx4 v[224:225], v[108:111], off nt
	global_store_dwordx4 v[224:225], v[104:107], off offset:64 nt
	global_store_dwordx4 v[224:225], v[100:103], off offset:512 nt
	global_store_dwordx4 v[224:225], v[96:99], off offset:576 nt
	v_add_u32_e32 v150, 128, v144
	v_ashrrev_i32_e32 v151, 31, v150
	v_lshlrev_b64 v[150:151], 13, v[150:151]
	v_lshl_add_u64 v[150:151], s[42:43], 0, v[150:151]
	v_lshl_add_u64 v[150:151], v[150:151], 0, v[146:147]
	v_mov_b32_e32 v224, v150
	v_mov_b32_e32 v225, v151
	global_load_dwordx4 v[172:175], v[150:151], off
	global_load_dwordx4 v[176:179], v[150:151], off offset:64
	global_load_dwordx4 v[180:183], v[150:151], off offset:512
	global_load_dwordx4 v[184:187], v[150:151], off offset:576
	s_waitcnt vmcnt(16)
	v_pk_add_f32 v[94:95], v[94:95], v[208:209]
	v_pk_add_f32 v[92:93], v[92:93], v[206:207]
	v_pk_add_f32 v[90:91], v[90:91], v[212:213]
	v_pk_add_f32 v[88:89], v[88:89], v[210:211]
	v_pk_add_f32 v[86:87], v[86:87], v[216:217]
	v_pk_add_f32 v[84:85], v[84:85], v[214:215]
	v_pk_add_f32 v[82:83], v[82:83], v[220:221]
	v_pk_add_f32 v[80:81], v[80:81], v[218:219]
	global_store_dwordx4 v[226:227], v[92:95], off nt
	global_store_dwordx4 v[226:227], v[88:91], off offset:64 nt
	global_store_dwordx4 v[226:227], v[84:87], off offset:512 nt
	global_store_dwordx4 v[226:227], v[80:83], off offset:576 nt
	v_add_u32_e32 v150, 144, v144
	v_ashrrev_i32_e32 v151, 31, v150
	v_lshlrev_b64 v[150:151], 13, v[150:151]
	v_lshl_add_u64 v[150:151], s[42:43], 0, v[150:151]
	v_lshl_add_u64 v[150:151], v[150:151], 0, v[146:147]
	v_mov_b32_e32 v226, v150
	v_mov_b32_e32 v227, v151
	global_load_dwordx4 v[206:209], v[150:151], off
	global_load_dwordx4 v[210:213], v[150:151], off offset:64
	global_load_dwordx4 v[214:217], v[150:151], off offset:512
	global_load_dwordx4 v[218:221], v[150:151], off offset:576
	s_waitcnt vmcnt(16)
;     __device__ __forceinline__ void operator()(const f32x4 (&acc)[2][2][4][2], const pg8::Unit& u, int wr, int wc, int fr, int fq) const {
;         const int row0 = u.pm * 256 + wr * 64 + fr, col0 = u.pn * 256 + wc * 32 + 4 * fq;
; #pragma unroll
;         for (int ai = 0; ai < 2; ++ai)
; #pragma unroll
;             for (int m = 0; m < 4; ++m) {
;                 const int row = row0 + ai * 128 + m * 16;
;                 float* rp = H + (size_t)row * DM + col0;
;                 float* op = OUT ? (OUT + (size_t)(row - NMETA) * DM + col0) : rp;
;                 const bool wr_ok = OUT ? (row >= NMETA && row < T_) : true;
; #pragma unroll
;                 for (int bj = 0; bj < 2; ++bj)
; #pragma unroll
;                     for (int n = 0; n < 2; ++n) {
;                         const f32x4 v = *(const f32x4*)(rp + bj * 128 + n * 16) + acc[ai][bj][m][n];
;                         if (wr_ok) __builtin_nontemporal_store(v, (f32x4*)(op + bj * 128 + n * 16));
;                     }
;             }
;     }
	v_pk_add_f32 v[78:79], v[78:79], v[158:159]
	v_pk_add_f32 v[76:77], v[76:77], v[156:157]
	v_pk_add_f32 v[74:75], v[74:75], v[162:163]
	v_pk_add_f32 v[72:73], v[72:73], v[160:161]
	v_pk_add_f32 v[70:71], v[70:71], v[166:167]
	v_pk_add_f32 v[68:69], v[68:69], v[164:165]
	v_pk_add_f32 v[66:67], v[66:67], v[170:171]
	v_pk_add_f32 v[64:65], v[64:65], v[168:169]
	global_store_dwordx4 v[222:223], v[76:79], off nt
	global_store_dwordx4 v[222:223], v[72:75], off offset:64 nt
	global_store_dwordx4 v[222:223], v[68:71], off offset:512 nt
	global_store_dwordx4 v[222:223], v[64:67], off offset:576 nt
	v_add_u32_e32 v150, 160, v144
	v_ashrrev_i32_e32 v151, 31, v150
	v_lshlrev_b64 v[150:151], 13, v[150:151]
	v_lshl_add_u64 v[150:151], s[42:43], 0, v[150:151]
	v_lshl_add_u64 v[150:151], v[150:151], 0, v[146:147]
	v_mov_b32_e32 v222, v150
	v_mov_b32_e32 v223, v151
	global_load_dwordx4 v[156:159], v[150:151], off
	global_load_dwordx4 v[160:163], v[150:151], off offset:64
	global_load_dwordx4 v[164:167], v[150:151], off offset:512
	global_load_dwordx4 v[168:171], v[150:151], off offset:576
	s_waitcnt vmcnt(16)
	v_pk_add_f32 v[62:63], v[62:63], v[174:175]
	v_pk_add_f32 v[60:61], v[60:61], v[172:173]
	v_pk_add_f32 v[58:59], v[58:59], v[178:179]
	v_pk_add_f32 v[56:57], v[56:57], v[176:177]
	v_pk_add_f32 v[54:55], v[54:55], v[182:183]
	v_pk_add_f32 v[52:53], v[52:53], v[180:181]
	v_pk_add_f32 v[50:51], v[50:51], v[186:187]
	v_pk_add_f32 v[48:49], v[48:49], v[184:185]
	global_store_dwordx4 v[224:225], v[60:63], off nt
	global_store_dwordx4 v[224:225], v[56:59], off offset:64 nt
	global_store_dwordx4 v[224:225], v[52:55], off offset:512 nt
	global_store_dwordx4 v[224:225], v[48:51], off offset:576 nt
	v_add_u32_e32 v150, 176, v144
	v_ashrrev_i32_e32 v151, 31, v150
	v_lshlrev_b64 v[150:151], 13, v[150:151]
	v_lshl_add_u64 v[150:151], s[42:43], 0, v[150:151]
	v_lshl_add_u64 v[150:151], v[150:151], 0, v[146:147]
	v_mov_b32_e32 v224, v150
	v_mov_b32_e32 v225, v151
	global_load_dwordx4 v[172:175], v[150:151], off
	global_load_dwordx4 v[176:179], v[150:151], off offset:64
	global_load_dwordx4 v[180:183], v[150:151], off offset:512
	global_load_dwordx4 v[184:187], v[150:151], off offset:576
	s_waitcnt vmcnt(16)
	v_pk_add_f32 v[46:47], v[46:47], v[208:209]
	v_pk_add_f32 v[44:45], v[44:45], v[206:207]
	v_pk_add_f32 v[42:43], v[42:43], v[212:213]
	v_pk_add_f32 v[40:41], v[40:41], v[210:211]
	v_pk_add_f32 v[38:39], v[38:39], v[216:217]
	v_pk_add_f32 v[36:37], v[36:37], v[214:215]
	v_pk_add_f32 v[34:35], v[34:35], v[220:221]
	v_pk_add_f32 v[32:33], v[32:33], v[218:219]
	global_store_dwordx4 v[226:227], v[44:47], off nt
	global_store_dwordx4 v[226:227], v[40:43], off offset:64 nt
	global_store_dwordx4 v[226:227], v[36:39], off offset:512 nt
	global_store_dwordx4 v[226:227], v[32:35], off offset:576 nt
	s_waitcnt vmcnt(12)
	v_pk_add_f32 v[30:31], v[30:31], v[158:159]
	v_pk_add_f32 v[28:29], v[28:29], v[156:157]
	v_pk_add_f32 v[26:27], v[26:27], v[162:163]
	v_pk_add_f32 v[24:25], v[24:25], v[160:161]
	v_pk_add_f32 v[22:23], v[22:23], v[166:167]
	v_pk_add_f32 v[20:21], v[20:21], v[164:165]
	v_pk_add_f32 v[18:19], v[18:19], v[170:171]
	v_pk_add_f32 v[16:17], v[16:17], v[168:169]
	global_store_dwordx4 v[222:223], v[28:31], off nt
	global_store_dwordx4 v[222:223], v[24:27], off offset:64 nt
	global_store_dwordx4 v[222:223], v[20:23], off offset:512 nt
	global_store_dwordx4 v[222:223], v[16:19], off offset:576 nt
	s_waitcnt vmcnt(8)
	v_pk_add_f32 v[14:15], v[14:15], v[174:175]
	v_pk_add_f32 v[12:13], v[12:13], v[172:173]
	v_pk_add_f32 v[10:11], v[10:11], v[178:179]
	v_pk_add_f32 v[8:9], v[8:9], v[176:177]
	v_pk_add_f32 v[6:7], v[6:7], v[182:183]
	v_pk_add_f32 v[4:5], v[4:5], v[180:181]
	v_pk_add_f32 v[2:3], v[2:3], v[186:187]
	v_pk_add_f32 v[0:1], v[0:1], v[184:185]
	global_store_dwordx4 v[224:225], v[12:15], off nt
	global_store_dwordx4 v[224:225], v[8:11], off offset:64 nt
	global_store_dwordx4 v[224:225], v[4:7], off offset:512 nt
	global_store_dwordx4 v[224:225], v[0:3], off offset:576 nt
	s_mov_b32 s3, 0x160000
	s_mov_b64 s[22:23], -1
	s_andn2_b64 vcc, exec, s[40:41]
	s_cbranch_vccnz .LBB0_107
	s_nop 0
	v_mov_b32_e32 v0, v149
	s_andn2_b64 vcc, exec, s[44:45]
	s_cbranch_vccnz .LBB0_106
	s_barrier
	s_branch .LBB0_106

; #define LAS __attribute__((address_space(3)))
; template <int NCH, class RB, class EP>
; __device__ __forceinline__ void tail_gemm(const bf16* A16, const bf16* Bt, int K, int ngroups, int vcu, int G, LAS unsigned char* lds, int wave, RB rb, EP ep) {
;     ...
; #pragma unroll 1
;     for (int g = vcu; g < ngroups; g += G) {
;         f32x4 acc[NCH];
; #pragma unroll
;         for (int c = 0; c < NCH; ++c) acc[c] = (f32x4){0.f, 0.f, 0.f, 0.f};
;         const bf16* ap = A16 + (size_t)r * K + wave * kw + 8 * q;
; #pragma unroll 2
;         for (int k = 0; k < kw; k += 32) {
;             const bf16x8 av = *(const bf16x8*)(ap + k);
; #pragma unroll
;             for (int c = 0; c < NCH; ++c) { const bf16x8 bv = *(const bf16x8*)(Bt + (size_t)(rb(g, c) + r) * K + wave * kw + 8 * q + k);
;                 acc[c] = __builtin_amdgcn_mfma_f32_16x16x32_bf16(av, bv, acc[c], 0, 0, 0); }
;         }
; #pragma unroll
;         for (int c = 0; c < NCH; ++c) *(LAS f32x4*)(red + (wave * NCH + c) * 256 + lane * 4) = acc[c];
;         __syncthreads();
; __global__ void __launch_bounds__(NTHR, 2) mk_fwd(Args a_byval) {
;     ...
;                 { float* H = (float*)(ws + WS_H);
;                   tail_gemm<1>((const bf16*)(ws + WS_MIX) + (size_t)8192 * DM, (const bf16*)(wl + OFF_WOUT), DM, DM / 16, vcu, G, lds, wave0,
;                       [](int g, int) { return g * 16; }, [=](int g, int r, int c, const float* v) { H[(size_t)(8192 + r) * DM + g * 16 + c] += v[0]; }); }
.LBB0_126:
	v_lshl_add_u64 v[18:19], v[14:15], 0, s[30:31]
	v_add_co_u32_e32 v26, vcc, 0x22c90000, v18
	v_lshl_add_u64 v[22:23], v[12:13], 0, s[30:31]
	s_nop 0
	v_addc_co_u32_e32 v27, vcc, 0, v19, vcc
	v_add_co_u32_e32 v28, vcc, 0x1280000, v22
	s_nop 1
	v_addc_co_u32_e32 v29, vcc, 0, v23, vcc
	global_load_dwordx4 v[64:67], v[26:27], off
	global_load_dwordx4 v[68:71], v[28:29], off
	global_load_dwordx4 v[72:75], v[26:27], off offset:64
	global_load_dwordx4 v[76:79], v[28:29], off offset:64
	global_load_dwordx4 v[80:83], v[26:27], off offset:128
	global_load_dwordx4 v[84:87], v[28:29], off offset:128
	global_load_dwordx4 v[88:91], v[26:27], off offset:192
	global_load_dwordx4 v[92:95], v[28:29], off offset:192
	global_load_dwordx4 v[96:99], v[26:27], off offset:256
	global_load_dwordx4 v[100:103], v[28:29], off offset:256
	global_load_dwordx4 v[104:107], v[26:27], off offset:320
	global_load_dwordx4 v[108:111], v[28:29], off offset:320
	global_load_dwordx4 v[112:115], v[26:27], off offset:384
	global_load_dwordx4 v[116:119], v[28:29], off offset:384
	global_load_dwordx4 v[120:123], v[26:27], off offset:448
	global_load_dwordx4 v[124:127], v[28:29], off offset:448
	s_waitcnt vmcnt(14)
	v_mfma_f32_16x16x32_bf16 v[0:3], v[64:67], v[68:71], v[0:3]
	s_waitcnt vmcnt(12)
	v_mfma_f32_16x16x32_bf16 v[0:3], v[72:75], v[76:79], v[0:3]
	s_waitcnt vmcnt(10)
	v_mfma_f32_16x16x32_bf16 v[0:3], v[80:83], v[84:87], v[0:3]
	s_waitcnt vmcnt(8)
	v_mfma_f32_16x16x32_bf16 v[0:3], v[88:91], v[92:95], v[0:3]
	s_waitcnt vmcnt(6)
	v_mfma_f32_16x16x32_bf16 v[0:3], v[96:99], v[100:103], v[0:3]
	s_waitcnt vmcnt(4)
	v_mfma_f32_16x16x32_bf16 v[0:3], v[104:107], v[108:111], v[0:3]
	s_waitcnt vmcnt(2)
	v_mfma_f32_16x16x32_bf16 v[0:3], v[112:115], v[116:119], v[0:3]
	s_waitcnt vmcnt(0)
	v_mfma_f32_16x16x32_bf16 v[0:3], v[120:123], v[124:127], v[0:3]
	s_nop 3
	s_nop 6
	ds_write_b128 v16, v[0:3]
	s_waitcnt lgkmcnt(0)
	s_barrier
	s_and_saveexec_b64 s[22:23], s[40:41]
	s_cbranch_execz .LBB0_124
	ds_read2st64_b32 v[0:1], v17 offset1:4
	s_lshl_b32 s18, s7, 4
	s_ashr_i32 s19, s18, 31
	s_waitcnt lgkmcnt(0)
	v_add_f32_e32 v0, 0, v0
	v_add_f32_e32 v2, v0, v1
	ds_read2st64_b32 v[0:1], v17 offset0:8 offset1:12
	s_waitcnt lgkmcnt(0)
	v_add_f32_e32 v0, v2, v0
	v_add_f32_e32 v2, v0, v1
	ds_read2st64_b32 v[0:1], v17 offset0:16 offset1:20
	s_waitcnt lgkmcnt(0)
	v_add_f32_e32 v0, v2, v0
	v_add_f32_e32 v2, v0, v1
	ds_read2st64_b32 v[0:1], v17 offset0:24 offset1:28
	s_waitcnt lgkmcnt(0)
	v_add_f32_e32 v0, v2, v0
	v_add_f32_e32 v2, v0, v1
	v_lshl_add_u64 v[0:1], s[18:19], 2, v[4:5]
	global_load_dword v3, v[0:1], off
	s_waitcnt vmcnt(0)
	v_add_f32_e32 v2, v2, v3
	global_store_dword v[0:1], v2, off
	s_branch .LBB0_124

; __device__ __forceinline__ void finishSM(f32x16& p0, f32x16& p1, float alpha, float& l_reg, bf16x8& pa0, bf16x8& pa1, bf16x8& pa2, bf16x8& pa3) {
; #pragma unroll
;     for (int r = 0; r < 16; ++r) p1[r] = __builtin_amdgcn_exp2f(p1[r]);
;     float ps = 0;
; #pragma unroll
;     for (int r = 0; r < 16; ++r) ps += p0[r];
; #pragma unroll
;     for (int r = 0; r < 16; ++r) ps += p1[r];
;     { auto rr = __builtin_amdgcn_permlane32_swap(__float_as_uint(ps), __float_as_uint(ps), false, false);
;       ps = __uint_as_float(rr[0]) + __uint_as_float(rr[1]); }
;     l_reg = l_reg * alpha + ps;
;     ...
;     PK4(p0, 0, pa0); PK4(p0, 8, pa1); PK4(p1, 0, pa2); PK4(p1, 8, pa3);
; __device__ __forceinline__ void qkt12(f32x16& p0, f32x16& p1, const char* Ks, const bf16x8* qr, int r32, int hi) {
;     p0 = f32x16{}; p1 = f32x16{};
; #pragma unroll
;     for (int d0 = 0; d0 < 12; ++d0) { const int cb = (d0 * 16 + hi * 8) * 2;
;         const bf16x8 b0 = *reinterpret_cast<const bf16x8*>(Ks + KSWZ(r32, cb));
;         const bf16x8 b1 = *reinterpret_cast<const bf16x8*>(Ks + KSWZ(32 + r32, cb));
;         p0 = __builtin_amdgcn_mfma_f32_32x32x16_bf16(b0, qr[d0], p0, 0, 0, 0);
;         p1 = __builtin_amdgcn_mfma_f32_32x32x16_bf16(b1, qr[d0], p1, 0, 0, 0); }
; }
.LBB0_172:
	s_add_i32 s3, s97, s76
	v_lshl_add_u64 v[176:177], s[16:17], 0, v[166:167]
	s_mov_b64 s[22:23], 0x25f90100
	v_lshl_add_u64 v[64:65], v[176:177], 0, s[22:23]
	s_mov_b32 m0, s3
	v_lshl_add_u64 v[178:179], s[16:17], 0, v[168:169]
	global_load_lds_dwordx4 v[64:65], off
	v_lshl_add_u64 v[64:65], v[178:179], 0, s[22:23]
	s_add_i32 m0, s3, 0x2000
	s_nop 0
	global_load_lds_dwordx4 v[64:65], off
	s_add_i32 s3, s55, 0
	v_add_u32_e32 v68, s3, v216
	ds_read_b128 v[64:67], v68
	ds_read_b128 v[68:71], v68 offset:12288
	v_add_u32_e32 v150, s3, v217
	ds_read_b128 v[248:251], v150
	ds_read_b128 v[150:153], v150 offset:12288
	v_add_u32_e32 v204, s3, v218
	ds_read_b128 v[200:203], v204
	ds_read_b128 v[204:207], v204 offset:12288
	s_waitcnt lgkmcnt(4)
	v_mfma_f32_32x32x16_bf16 v[80:95], v[64:67], v[96:99], 0
	v_exp_f32_e32 v194, v144
	v_add_f32_e32 v144, 0, v244
	v_add_f32_e32 v144, v246, v144
	v_add_f32_e32 v144, v242, v144
	v_add_f32_e32 v144, v245, v144
	v_add_f32_e32 v144, v241, v144
	v_add_f32_e32 v144, v243, v144
	v_mfma_f32_32x32x16_bf16 v[64:79], v[68:71], v[96:99], 0
	v_add_f32_e32 v144, v239, v144
	v_add_f32_e32 v144, v240, v144
	v_add_f32_e32 v144, v236, v144
	v_add_f32_e32 v144, v238, v144
	v_add_f32_e32 v144, v235, v144
	v_add_f32_e32 v144, v237, v144
	v_exp_f32_e32 v190, v190
	s_waitcnt lgkmcnt(2)
	v_mfma_f32_32x32x16_bf16 v[64:79], v[150:153], v[100:103], v[64:79]
	v_add_f32_e32 v144, v232, v144
	v_exp_f32_e32 v191, v191
	v_add_f32_e32 v144, v234, v144
	v_exp_f32_e32 v188, v188
	v_add_f32_e32 v144, v231, v144
	v_exp_f32_e32 v189, v189
	v_add_f32_e32 v144, v233, v144
	v_mfma_f32_32x32x16_bf16 v[80:95], v[248:251], v[100:103], v[80:95]
	v_add_u32_e32 v247, s3, v219
	ds_read_b128 v[150:153], v247
	ds_read_b128 v[248:251], v247 offset:12288
	v_exp_f32_e32 v186, v186
	v_add_f32_e32 v144, v190, v144
	v_exp_f32_e32 v187, v187
	v_add_f32_e32 v144, v191, v144
	v_add_f32_e32 v144, v188, v144
	s_waitcnt lgkmcnt(2)
	v_mfma_f32_32x32x16_bf16 v[64:79], v[204:207], v[104:107], v[64:79]
	v_exp_f32_e32 v185, v185
	v_add_f32_e32 v144, v189, v144
	v_add_f32_e32 v144, v186, v144
	v_add_f32_e32 v144, v187, v144
	v_exp_f32_e32 v252, v146
	v_exp_f32_e32 v197, v147
	v_exp_f32_e32 v195, v145
	v_mfma_f32_32x32x16_bf16 v[80:95], v[200:203], v[104:107], v[80:95]
	v_add_u32_e32 v204, s3, v220
	ds_read_b128 v[200:203], v204
	ds_read_b128 v[204:207], v204 offset:12288
	s_waitcnt lgkmcnt(2)
	v_mfma_f32_32x32x16_bf16 v[64:79], v[248:251], v[108:111], v[64:79]
	v_mfma_f32_32x32x16_bf16 v[80:95], v[150:153], v[108:111], v[80:95]
	v_add_u32_e32 v247, s3, v221
	ds_read_b128 v[150:153], v247
	ds_read_b128 v[248:251], v247 offset:12288
	s_waitcnt lgkmcnt(2)
	v_mfma_f32_32x32x16_bf16 v[64:79], v[204:207], v[112:115], v[64:79]
	v_mfma_f32_32x32x16_bf16 v[80:95], v[200:203], v[112:115], v[80:95]
	v_add_u32_e32 v204, s3, v222
	ds_read_b128 v[200:203], v204
	ds_read_b128 v[204:207], v204 offset:12288
	s_waitcnt lgkmcnt(2)
	v_mfma_f32_32x32x16_bf16 v[64:79], v[248:251], v[116:119], v[64:79]
	v_mfma_f32_32x32x16_bf16 v[80:95], v[150:153], v[116:119], v[80:95]
	v_add_u32_e32 v247, s3, v223
	ds_read_b128 v[150:153], v247
	ds_read_b128 v[248:251], v247 offset:12288
	s_waitcnt lgkmcnt(2)
	v_mfma_f32_32x32x16_bf16 v[64:79], v[204:207], v[120:123], v[64:79]
	v_mfma_f32_32x32x16_bf16 v[80:95], v[200:203], v[120:123], v[80:95]
	v_add_u32_e32 v204, s3, v224
	ds_read_b128 v[200:203], v204
	ds_read_b128 v[204:207], v204 offset:12288
	s_waitcnt lgkmcnt(2)
	v_mfma_f32_32x32x16_bf16 v[64:79], v[248:251], v[124:127], v[64:79]
	v_mfma_f32_32x32x16_bf16 v[80:95], v[150:153], v[124:127], v[80:95]
	v_add_u32_e32 v247, s3, v225
	ds_read_b128 v[150:153], v247
	ds_read_b128 v[248:251], v247 offset:12288
	s_waitcnt lgkmcnt(2)
	v_mfma_f32_32x32x16_bf16 v[64:79], v[204:207], v[128:131], v[64:79]
	v_mfma_f32_32x32x16_bf16 v[80:95], v[200:203], v[128:131], v[80:95]
	v_add_u32_e32 v204, s3, v226
	ds_read_b128 v[200:203], v204
	ds_read_b128 v[204:207], v204 offset:12288
	s_waitcnt lgkmcnt(2)
	v_mfma_f32_32x32x16_bf16 v[64:79], v[248:251], v[132:135], v[64:79]
	v_mfma_f32_32x32x16_bf16 v[80:95], v[150:153], v[132:135], v[80:95]
	v_add_u32_e32 v247, s3, v228
	ds_read_b128 v[150:153], v247
	ds_read_b128 v[248:251], v247 offset:12288
	s_waitcnt lgkmcnt(2)
	v_mfma_f32_32x32x16_bf16 v[64:79], v[204:207], v[136:139], v[64:79]
	v_mfma_f32_32x32x16_bf16 v[80:95], v[200:203], v[136:139], v[80:95]
	v_exp_f32_e32 v247, v184
	s_nop 0
	v_add_f32_e32 v144, v247, v144
	v_add_f32_e32 v144, v185, v144
	s_waitcnt lgkmcnt(0)
	v_mfma_f32_32x32x16_bf16 v[64:79], v[248:251], v[140:143], v[64:79]
	v_exp_f32_e32 v248, v182
	v_exp_f32_e32 v249, v183
	v_exp_f32_e32 v250, v180
	v_exp_f32_e32 v251, v181
	v_add_f32_e32 v144, v248, v144
	v_add_f32_e32 v144, v249, v144
	v_add_f32_e32 v144, v250, v144
	v_mfma_f32_32x32x16_bf16 v[80:95], v[150:153], v[140:143], v[80:95]
	v_add_f32_e32 v144, v251, v144
	v_add_f32_e32 v144, v252, v144
	v_add_f32_e32 v144, v197, v144
	v_add_f32_e32 v144, v194, v144
	v_add_f32_e32 v180, v195, v144
	v_mov_b32_e32 v181, v180
	v_cvt_pk_bf16_f32 v144, v244, v246
	v_cvt_pk_bf16_f32 v145, v242, v245
	v_cvt_pk_bf16_f32 v146, v241, v243
	v_cvt_pk_bf16_f32 v147, v239, v240
	s_nop 1
	v_permlane32_swap_b32_e32 v180, v181
	v_permlane32_swap_b32_e32 v144, v146
	v_permlane32_swap_b32_e32 v145, v147
	v_cvt_pk_bf16_f32 v150, v236, v238
	v_cvt_pk_bf16_f32 v151, v235, v237
	v_cvt_pk_bf16_f32 v152, v232, v234
	v_cvt_pk_bf16_f32 v153, v231, v233
	v_cvt_pk_bf16_f32 v182, v190, v191
	v_cvt_pk_bf16_f32 v183, v188, v189
	v_cvt_pk_bf16_f32 v184, v186, v187
	v_cvt_pk_bf16_f32 v185, v247, v185
	v_cvt_pk_bf16_f32 v186, v248, v249
	v_cvt_pk_bf16_f32 v187, v250, v251
	v_cvt_pk_bf16_f32 v188, v252, v197
	v_cvt_pk_bf16_f32 v189, v194, v195
	s_nop 0
	v_permlane32_swap_b32_e32 v150, v152
	v_permlane32_swap_b32_e32 v151, v153
	v_permlane32_swap_b32_e32 v182, v184
	v_permlane32_swap_b32_e32 v183, v185
	v_permlane32_swap_b32_e32 v186, v188
	v_permlane32_swap_b32_e32 v187, v189
	v_add_u32_e32 v190, s19, v227
	ds_read_b64_tr_b16 v[232:233], v190 offset:0
	ds_read_b64_tr_b16 v[234:235], v190 offset:0x800
	ds_read_b64_tr_b16 v[236:237], v190 offset:0x1000
	ds_read_b64_tr_b16 v[238:239], v190 offset:0x1800
	ds_read_b64_tr_b16 v[240:241], v190 offset:0x2000
	ds_read_b64_tr_b16 v[242:243], v190 offset:0x2800
	ds_read_b64_tr_b16 v[244:245], v190 offset:0x3000
	ds_read_b64_tr_b16 v[246:247], v190 offset:0x3800
	s_waitcnt lgkmcnt(0)
; #define SBAR() __builtin_amdgcn_sched_barrier(0)
; __device__ __forceinline__ void partialSM_ref(f32x16& p0, f32x16& p1, float& m_reg, float& mn, float& alpha, float pmax) {
;     constexpr float C = SCALE * 1.4426950408889634f;
;     if (__builtin_expect(__all(pmax - m_reg <= THR / SCALE), 1)) { mn = m_reg; alpha = 1.f; }
;     else { mn = fmaxf(m_reg, pmax); alpha = __builtin_amdgcn_exp2f((m_reg - mn) * C); m_reg = mn; }
; template <int D0> __device__ __forceinline__ void pv_one(f32x16& od, int vb, bf16x8 pa0, bf16x8 pa1, bf16x8 pa2, bf16x8 pa3) {
;     const s16x4 l0 = tr_read<v_rd_off(D0, 0, 0)>(vb), h0 = tr_read<v_rd_off(D0, 0, 1)>(vb), l1 = tr_read<v_rd_off(D0, 1, 0)>(vb), h1 = tr_read<v_rd_off(D0, 1, 1)>(vb);
;     const s16x4 l2 = tr_read<v_rd_off(D0, 2, 0)>(vb), h2 = tr_read<v_rd_off(D0, 2, 1)>(vb), l3 = tr_read<v_rd_off(D0, 3, 0)>(vb), h3 = tr_read<v_rd_off(D0, 3, 1)>(vb);
;     asm volatile("s_waitcnt lgkmcnt(0)" ::: "memory"); SBAR();
;     ...
;     od = __builtin_amdgcn_mfma_f32_32x32x16_bf16(pa0, PK(l0, h0), od, 0, 0, 0);
;     od = __builtin_amdgcn_mfma_f32_32x32x16_bf16(pa1, PK(l1, h1), od, 0, 0, 0);
;     od = __builtin_amdgcn_mfma_f32_32x32x16_bf16(pa2, PK(l2, h2), od, 0, 0, 0);
;     od = __builtin_amdgcn_mfma_f32_32x32x16_bf16(pa3, PK(l3, h3), od, 0, 0, 0);
;     ...
; }
; __device__ __forceinline__ void pv_d0(f32x16* o, int vb, bf16x8 pa0, bf16x8 pa1, bf16x8 pa2, bf16x8 pa3) {
;     pv_one<0>(o[0], vb, pa0, pa1, pa2, pa3); pv_one<1>(o[1], vb, pa0, pa1, pa2, pa3); pv_one<2>(o[2], vb, pa0, pa1, pa2, pa3); pv_one<3>(o[3], vb, pa0, pa1, pa2, pa3);
; }
	s_nop 0
	v_mfma_f32_32x32x16_bf16 v[0:15], v[144:147], v[232:235], v[0:15]
	ds_read_b64_tr_b16 v[232:233], v190 offset:0x200
	ds_read_b64_tr_b16 v[234:235], v190 offset:0xa00
	v_mfma_f32_32x32x16_bf16 v[0:15], v[150:153], v[236:239], v[0:15]
	ds_read_b64_tr_b16 v[236:237], v190 offset:0x1200
	ds_read_b64_tr_b16 v[238:239], v190 offset:0x1a00
	v_mfma_f32_32x32x16_bf16 v[0:15], v[182:185], v[240:243], v[0:15]
	ds_read_b64_tr_b16 v[240:241], v190 offset:0x2200
	ds_read_b64_tr_b16 v[242:243], v190 offset:0x2a00
	v_mfma_f32_32x32x16_bf16 v[0:15], v[186:189], v[244:247], v[0:15]
	ds_read_b64_tr_b16 v[244:245], v190 offset:0x3200
	ds_read_b64_tr_b16 v[246:247], v190 offset:0x3a00
	s_waitcnt lgkmcnt(0)
	v_mfma_f32_32x32x16_bf16 v[48:63], v[144:147], v[232:235], v[48:63]
	ds_read_b64_tr_b16 v[232:233], v190 offset:0x400
	ds_read_b64_tr_b16 v[234:235], v190 offset:0xc00
	v_mfma_f32_32x32x16_bf16 v[48:63], v[150:153], v[236:239], v[48:63]
	ds_read_b64_tr_b16 v[236:237], v190 offset:0x1400
	ds_read_b64_tr_b16 v[238:239], v190 offset:0x1c00
	v_mfma_f32_32x32x16_bf16 v[48:63], v[182:185], v[240:243], v[48:63]
	ds_read_b64_tr_b16 v[240:241], v190 offset:0x2400
	ds_read_b64_tr_b16 v[242:243], v190 offset:0x2c00
	v_mfma_f32_32x32x16_bf16 v[48:63], v[186:189], v[244:247], v[48:63]
	ds_read_b64_tr_b16 v[244:245], v190 offset:0x3400
	ds_read_b64_tr_b16 v[246:247], v190 offset:0x3c00
	s_waitcnt lgkmcnt(0)
	v_mfma_f32_32x32x16_bf16 v[32:47], v[144:147], v[232:235], v[32:47]
	ds_read_b64_tr_b16 v[232:233], v190 offset:0x600
	ds_read_b64_tr_b16 v[234:235], v190 offset:0xe00
	v_mfma_f32_32x32x16_bf16 v[32:47], v[150:153], v[236:239], v[32:47]
	ds_read_b64_tr_b16 v[236:237], v190 offset:0x1600
	ds_read_b64_tr_b16 v[238:239], v190 offset:0x1e00
	v_mfma_f32_32x32x16_bf16 v[32:47], v[182:185], v[240:243], v[32:47]
	ds_read_b64_tr_b16 v[240:241], v190 offset:0x2600
	ds_read_b64_tr_b16 v[242:243], v190 offset:0x2e00
	v_mfma_f32_32x32x16_bf16 v[32:47], v[186:189], v[244:247], v[32:47]
	ds_read_b64_tr_b16 v[244:245], v190 offset:0x3600
	ds_read_b64_tr_b16 v[246:247], v190 offset:0x3e00
	s_waitcnt lgkmcnt(0)
	v_mfma_f32_32x32x16_bf16 v[16:31], v[144:147], v[232:235], v[16:31]
	v_max_f32_e64 v145, s7, s7
	v_max_f32_e32 v146, v230, v230
	v_max_f32_e32 v146, v146, v145
	v_sub_f32_e32 v147, v230, v146
	v_mul_f32_e32 v147, 0x3dd53b94, v147
	v_sub_f32_e32 v144, s7, v230
	v_exp_f32_e32 v147, v147
	v_mfma_f32_32x32x16_bf16 v[16:31], v[150:153], v[236:239], v[16:31]
	v_cmp_ge_f32_e32 vcc, s0, v144
	s_cmp_eq_u64 vcc, exec
	s_cselect_b64 s[48:49], -1, 0
	v_cndmask_b32_e64 v144, v147, 1.0, s[48:49]
	v_cmp_gt_f32_e32 vcc, 1.0, v144
	v_mfma_f32_32x32x16_bf16 v[16:31], v[182:185], v[240:243], v[16:31]
	v_mfma_f32_32x32x16_bf16 v[16:31], v[186:189], v[244:247], v[16:31]
	s_cbranch_vccz .LBB0_176
	s_and_saveexec_b64 s[22:23], s[42:43]
	ds_write_b32 v157, v144 offset:128
	s_or_b64 exec, exec, s[22:23]
	s_waitcnt lgkmcnt(0)
	v_add_u32_e32 v147, s89, v148
	ds_read_b128 v[150:153], v147 offset:224
	ds_read_b128 v[182:185], v147 offset:192
	ds_read_b128 v[186:189], v147 offset:160
	ds_read_b128 v[232:235], v147 offset:128
	s_waitcnt lgkmcnt(0)
	v_pk_mul_f32 v[12:13], v[12:13], v[150:151]
	v_pk_mul_f32 v[8:9], v[8:9], v[182:183]
	v_pk_mul_f32 v[4:5], v[4:5], v[186:187]
	v_pk_mul_f32 v[14:15], v[14:15], v[152:153]
	v_pk_mul_f32 v[10:11], v[10:11], v[184:185]
	v_pk_mul_f32 v[6:7], v[6:7], v[188:189]
	v_pk_mul_f32 v[2:3], v[2:3], v[234:235]
	v_pk_mul_f32 v[0:1], v[0:1], v[232:233]
	v_pk_mul_f32 v[60:61], v[60:61], v[150:151]
	v_pk_mul_f32 v[56:57], v[56:57], v[182:183]
	v_pk_mul_f32 v[52:53], v[52:53], v[186:187]
	v_pk_mul_f32 v[62:63], v[62:63], v[152:153]
	v_pk_mul_f32 v[58:59], v[58:59], v[184:185]
	v_pk_mul_f32 v[54:55], v[54:55], v[188:189]
	v_pk_mul_f32 v[50:51], v[50:51], v[234:235]
	v_pk_mul_f32 v[48:49], v[48:49], v[232:233]
	v_pk_mul_f32 v[44:45], v[44:45], v[150:151]
	v_pk_mul_f32 v[40:41], v[40:41], v[182:183]
	v_pk_mul_f32 v[36:37], v[36:37], v[186:187]
	v_pk_mul_f32 v[46:47], v[46:47], v[152:153]
	v_pk_mul_f32 v[42:43], v[42:43], v[184:185]
	v_pk_mul_f32 v[38:39], v[38:39], v[188:189]
	v_pk_mul_f32 v[34:35], v[34:35], v[234:235]
	v_pk_mul_f32 v[32:33], v[32:33], v[232:233]
	v_pk_mul_f32 v[28:29], v[28:29], v[150:151]
	v_pk_mul_f32 v[24:25], v[24:25], v[182:183]
	v_pk_mul_f32 v[20:21], v[20:21], v[186:187]
	v_pk_mul_f32 v[30:31], v[30:31], v[152:153]
	v_pk_mul_f32 v[26:27], v[26:27], v[184:185]
	v_pk_mul_f32 v[22:23], v[22:23], v[188:189]
	v_pk_mul_f32 v[18:19], v[18:19], v[234:235]
	v_pk_mul_f32 v[16:17], v[16:17], v[232:233]

; __device__ __forceinline__ void partialSM_ref(f32x16& p0, f32x16& p1, float& m_reg, float& mn, float& alpha, float pmax) {
;     ...
;     const float mnC = -mn * C;
; #pragma unroll
;     for (int r = 0; r < 16; ++r) p0[r] = fmaf(p0[r], C, mnC);
; #pragma unroll
;     for (int r = 0; r < 16; ++r) p1[r] = fmaf(p1[r], C, mnC);
; #pragma unroll
;     for (int r = 0; r < 16; ++r) p0[r] = __builtin_amdgcn_exp2f(p0[r]);
; __device__ __forceinline__ void qkt12(f32x16& p0, f32x16& p1, const char* Ks, const bf16x8* qr, int r32, int hi) {
;     p0 = f32x16{}; p1 = f32x16{};
; #pragma unroll
;     for (int d0 = 0; d0 < 12; ++d0) { const int cb = (d0 * 16 + hi * 8) * 2;
;         const bf16x8 b0 = *reinterpret_cast<const bf16x8*>(Ks + KSWZ(r32, cb));
;         const bf16x8 b1 = *reinterpret_cast<const bf16x8*>(Ks + KSWZ(32 + r32, cb));
;         p0 = __builtin_amdgcn_mfma_f32_32x32x16_bf16(b0, qr[d0], p0, 0, 0, 0);
;         p1 = __builtin_amdgcn_mfma_f32_32x32x16_bf16(b1, qr[d0], p1, 0, 0, 0); }
; }
.LBB0_184:
	v_cndmask_b32_e64 v146, v146, v230, s[48:49]
	v_mul_f32_e32 v147, 0xbdd53b94, v146
	v_fmamk_f32 v80, v80, 0x3dd53b94, v147
	v_fmamk_f32 v81, v81, 0x3dd53b94, v147
	v_fmamk_f32 v82, v82, 0x3dd53b94, v147
	v_fmamk_f32 v83, v83, 0x3dd53b94, v147
	v_fmamk_f32 v84, v84, 0x3dd53b94, v147
	v_fmamk_f32 v85, v85, 0x3dd53b94, v147
	v_fmamk_f32 v86, v86, 0x3dd53b94, v147
	v_fmamk_f32 v87, v87, 0x3dd53b94, v147
	v_fmamk_f32 v88, v88, 0x3dd53b94, v147
	v_fmamk_f32 v89, v89, 0x3dd53b94, v147
	v_fmamk_f32 v90, v90, 0x3dd53b94, v147
	v_fmamk_f32 v91, v91, 0x3dd53b94, v147
	v_fmamk_f32 v92, v92, 0x3dd53b94, v147
	v_fmamk_f32 v93, v93, 0x3dd53b94, v147
	v_fmamk_f32 v94, v94, 0x3dd53b94, v147
	v_fmamk_f32 v95, v95, 0x3dd53b94, v147
	v_fmamk_f32 v174, v64, 0x3dd53b94, v147
	v_fmamk_f32 v175, v65, 0x3dd53b94, v147
	v_fmamk_f32 v176, v66, 0x3dd53b94, v147
	v_fmamk_f32 v177, v67, 0x3dd53b94, v147
	v_fmamk_f32 v178, v68, 0x3dd53b94, v147
	v_fmamk_f32 v179, v69, 0x3dd53b94, v147
	v_fmamk_f32 v182, v70, 0x3dd53b94, v147
	v_fmamk_f32 v183, v71, 0x3dd53b94, v147
	v_fmamk_f32 v184, v72, 0x3dd53b94, v147
	v_fmamk_f32 v185, v73, 0x3dd53b94, v147
	v_fmamk_f32 v186, v74, 0x3dd53b94, v147
	v_fmamk_f32 v187, v75, 0x3dd53b94, v147
	v_fmamk_f32 v188, v76, 0x3dd53b94, v147
	v_fmamk_f32 v240, v77, 0x3dd53b94, v147
	v_fmamk_f32 v241, v78, 0x3dd53b94, v147
	v_fmac_f32_e32 v147, 0x3dd53b94, v79
	v_exp_f32_e32 v189, v80
	v_exp_f32_e32 v190, v81
	v_exp_f32_e32 v191, v82
	v_exp_f32_e32 v194, v83
	v_exp_f32_e32 v195, v84
	v_exp_f32_e32 v197, v85
	v_exp_f32_e32 v230, v86
	v_exp_f32_e32 v231, v87
	v_exp_f32_e32 v232, v88
	v_exp_f32_e32 v233, v89
	v_exp_f32_e32 v234, v90
	v_exp_f32_e32 v235, v91
	v_exp_f32_e32 v236, v92
	v_exp_f32_e32 v237, v93
	v_exp_f32_e32 v238, v94
	v_exp_f32_e32 v239, v95
	s_add_i32 s3, s77, 0
	v_add_u32_e32 v68, s3, v216
	ds_read_b128 v[64:67], v68
	ds_read_b128 v[68:71], v68 offset:12288
	v_add_u32_e32 v170, s3, v217
	ds_read_b128 v[150:153], v170
	ds_read_b128 v[170:173], v170 offset:12288
	v_add_u32_e32 v204, s3, v218
	ds_read_b128 v[200:203], v204
	ds_read_b128 v[204:207], v204 offset:12288
	v_exp_f32_e32 v244, v147
	s_waitcnt lgkmcnt(4)
	v_mfma_f32_32x32x16_bf16 v[80:95], v[64:67], v[96:99], 0
	v_add_f32_e32 v147, 0, v189
	v_add_f32_e32 v147, v190, v147
	v_add_f32_e32 v147, v191, v147
	v_add_f32_e32 v147, v194, v147
	v_add_f32_e32 v147, v195, v147
	v_add_f32_e32 v147, v197, v147
	v_add_f32_e32 v147, v230, v147
	v_mfma_f32_32x32x16_bf16 v[64:79], v[68:71], v[96:99], 0
	v_add_f32_e32 v147, v231, v147
	v_add_f32_e32 v147, v232, v147
	v_add_f32_e32 v147, v233, v147
	v_add_f32_e32 v147, v234, v147
	v_add_f32_e32 v147, v235, v147
	v_add_f32_e32 v147, v236, v147
	v_exp_f32_e32 v242, v175
	s_waitcnt lgkmcnt(2)
	v_mfma_f32_32x32x16_bf16 v[64:79], v[170:173], v[100:103], v[64:79]
	v_add_f32_e32 v147, v237, v147
	v_exp_f32_e32 v243, v176
	v_add_f32_e32 v147, v238, v147
	v_exp_f32_e32 v177, v177
	v_add_f32_e32 v147, v239, v147
	v_exp_f32_e32 v178, v178
	v_mfma_f32_32x32x16_bf16 v[80:95], v[150:153], v[100:103], v[80:95]
	v_add_u32_e32 v170, s3, v219
	ds_read_b128 v[150:153], v170
	ds_read_b128 v[170:173], v170 offset:12288
	v_exp_f32_e32 v179, v179
	v_exp_f32_e32 v182, v182
	v_exp_f32_e32 v183, v183
	v_exp_f32_e32 v184, v184
	v_exp_f32_e32 v185, v185
	v_exp_f32_e32 v186, v186
	s_waitcnt lgkmcnt(2)
	v_mfma_f32_32x32x16_bf16 v[64:79], v[204:207], v[104:107], v[64:79]
	v_exp_f32_e32 v187, v187
	v_exp_f32_e32 v188, v188
	v_exp_f32_e32 v240, v240
	v_exp_f32_e32 v241, v241
	v_mfma_f32_32x32x16_bf16 v[80:95], v[200:203], v[104:107], v[80:95]
	v_add_u32_e32 v204, s3, v220
	ds_read_b128 v[200:203], v204
	ds_read_b128 v[204:207], v204 offset:12288
	s_waitcnt lgkmcnt(2)
	v_mfma_f32_32x32x16_bf16 v[64:79], v[170:173], v[108:111], v[64:79]
	v_mfma_f32_32x32x16_bf16 v[80:95], v[150:153], v[108:111], v[80:95]
	v_add_u32_e32 v170, s3, v221
	ds_read_b128 v[150:153], v170
	ds_read_b128 v[170:173], v170 offset:12288
	s_waitcnt lgkmcnt(2)
	v_mfma_f32_32x32x16_bf16 v[64:79], v[204:207], v[112:115], v[64:79]
	v_mfma_f32_32x32x16_bf16 v[80:95], v[200:203], v[112:115], v[80:95]
	v_add_u32_e32 v204, s3, v222
	ds_read_b128 v[200:203], v204
	ds_read_b128 v[204:207], v204 offset:12288
	s_waitcnt lgkmcnt(2)
	v_mfma_f32_32x32x16_bf16 v[64:79], v[170:173], v[116:119], v[64:79]
	v_mfma_f32_32x32x16_bf16 v[80:95], v[150:153], v[116:119], v[80:95]
	v_add_u32_e32 v170, s3, v223
	ds_read_b128 v[150:153], v170
	ds_read_b128 v[170:173], v170 offset:12288
	s_waitcnt lgkmcnt(2)
	v_mfma_f32_32x32x16_bf16 v[64:79], v[204:207], v[120:123], v[64:79]
	v_mfma_f32_32x32x16_bf16 v[80:95], v[200:203], v[120:123], v[80:95]
	v_add_u32_e32 v204, s3, v224
	ds_read_b128 v[200:203], v204
	ds_read_b128 v[204:207], v204 offset:12288
	s_waitcnt lgkmcnt(2)
	v_mfma_f32_32x32x16_bf16 v[64:79], v[170:173], v[124:127], v[64:79]
	v_mfma_f32_32x32x16_bf16 v[80:95], v[150:153], v[124:127], v[80:95]
	v_add_u32_e32 v170, s3, v225
	ds_read_b128 v[150:153], v170
	ds_read_b128 v[170:173], v170 offset:12288
	s_waitcnt lgkmcnt(2)
	v_mfma_f32_32x32x16_bf16 v[64:79], v[204:207], v[128:131], v[64:79]
	v_mfma_f32_32x32x16_bf16 v[80:95], v[200:203], v[128:131], v[80:95]
	v_add_u32_e32 v204, s3, v226
	ds_read_b128 v[200:203], v204
	ds_read_b128 v[204:207], v204 offset:12288
	s_waitcnt lgkmcnt(2)
	v_mfma_f32_32x32x16_bf16 v[64:79], v[170:173], v[132:135], v[64:79]
	v_mfma_f32_32x32x16_bf16 v[80:95], v[150:153], v[132:135], v[80:95]
	v_add_u32_e32 v170, s3, v228
	ds_read_b128 v[150:153], v170
	ds_read_b128 v[170:173], v170 offset:12288
	s_waitcnt lgkmcnt(2)
; #define SBAR() __builtin_amdgcn_sched_barrier(0)
; __device__ __forceinline__ void finishSM(f32x16& p0, f32x16& p1, float alpha, float& l_reg, bf16x8& pa0, bf16x8& pa1, bf16x8& pa2, bf16x8& pa3) {
; #pragma unroll
;     for (int r = 0; r < 16; ++r) p1[r] = __builtin_amdgcn_exp2f(p1[r]);
;     float ps = 0;
; #pragma unroll
;     for (int r = 0; r < 16; ++r) ps += p0[r];
; #pragma unroll
;     for (int r = 0; r < 16; ++r) ps += p1[r];
;     { auto rr = __builtin_amdgcn_permlane32_swap(__float_as_uint(ps), __float_as_uint(ps), false, false);
;       ps = __uint_as_float(rr[0]) + __uint_as_float(rr[1]); }
;     l_reg = l_reg * alpha + ps;
;     ...
;     PK4(p0, 0, pa0); PK4(p0, 8, pa1); PK4(p1, 0, pa2); PK4(p1, 8, pa3);
; template <int D0> __device__ __forceinline__ void pv_one(f32x16& od, int vb, bf16x8 pa0, bf16x8 pa1, bf16x8 pa2, bf16x8 pa3) {
;     const s16x4 l0 = tr_read<v_rd_off(D0, 0, 0)>(vb), h0 = tr_read<v_rd_off(D0, 0, 1)>(vb), l1 = tr_read<v_rd_off(D0, 1, 0)>(vb), h1 = tr_read<v_rd_off(D0, 1, 1)>(vb);
;     const s16x4 l2 = tr_read<v_rd_off(D0, 2, 0)>(vb), h2 = tr_read<v_rd_off(D0, 2, 1)>(vb), l3 = tr_read<v_rd_off(D0, 3, 0)>(vb), h3 = tr_read<v_rd_off(D0, 3, 1)>(vb);
;     asm volatile("s_waitcnt lgkmcnt(0)" ::: "memory"); SBAR();
;     ...
;     od = __builtin_amdgcn_mfma_f32_32x32x16_bf16(pa0, PK(l0, h0), od, 0, 0, 0);
;     od = __builtin_amdgcn_mfma_f32_32x32x16_bf16(pa1, PK(l1, h1), od, 0, 0, 0);
;     od = __builtin_amdgcn_mfma_f32_32x32x16_bf16(pa2, PK(l2, h2), od, 0, 0, 0);
;     od = __builtin_amdgcn_mfma_f32_32x32x16_bf16(pa3, PK(l3, h3), od, 0, 0, 0);
;     ...
; }
; __device__ __forceinline__ void pv_d0(f32x16* o, int vb, bf16x8 pa0, bf16x8 pa1, bf16x8 pa2, bf16x8 pa3) {
;     pv_one<0>(o[0], vb, pa0, pa1, pa2, pa3); pv_one<1>(o[1], vb, pa0, pa1, pa2, pa3); pv_one<2>(o[2], vb, pa0, pa1, pa2, pa3); pv_one<3>(o[3], vb, pa0, pa1, pa2, pa3);
; }
	v_mfma_f32_32x32x16_bf16 v[64:79], v[204:207], v[136:139], v[64:79]
	v_mfma_f32_32x32x16_bf16 v[80:95], v[200:203], v[136:139], v[80:95]
	s_waitcnt lgkmcnt(0)
	v_mfma_f32_32x32x16_bf16 v[64:79], v[170:173], v[140:143], v[64:79]
	v_exp_f32_e32 v170, v174
	s_nop 0
	v_add_f32_e32 v147, v170, v147
	v_add_f32_e32 v147, v242, v147
	v_add_f32_e32 v147, v243, v147
	v_add_f32_e32 v147, v177, v147
	v_add_f32_e32 v147, v178, v147
	v_add_f32_e32 v147, v179, v147
	v_add_f32_e32 v147, v182, v147
	v_add_f32_e32 v147, v183, v147
	v_add_f32_e32 v147, v184, v147
	v_add_f32_e32 v147, v185, v147
	v_mfma_f32_32x32x16_bf16 v[80:95], v[150:153], v[140:143], v[80:95]
	v_add_f32_e32 v147, v186, v147
	v_add_f32_e32 v147, v187, v147
	v_add_f32_e32 v147, v188, v147
	v_add_f32_e32 v147, v240, v147
	v_add_f32_e32 v147, v241, v147
	v_add_f32_e32 v147, v244, v147
	v_mov_b32_e32 v171, v147
	s_nop 1
	v_permlane32_swap_b32_e32 v147, v171
	v_cvt_pk_bf16_f32 v150, v189, v190
	v_cvt_pk_bf16_f32 v151, v191, v194
	v_cvt_pk_bf16_f32 v152, v195, v197
	v_cvt_pk_bf16_f32 v153, v230, v231
	v_cvt_pk_bf16_f32 v172, v232, v233
	v_cvt_pk_bf16_f32 v173, v234, v235
	v_cvt_pk_bf16_f32 v174, v236, v237
	v_cvt_pk_bf16_f32 v175, v238, v239
	v_cvt_pk_bf16_f32 v176, v170, v242
	v_cvt_pk_bf16_f32 v177, v243, v177
	v_cvt_pk_bf16_f32 v178, v178, v179
	v_cvt_pk_bf16_f32 v179, v182, v183
	v_cvt_pk_bf16_f32 v182, v184, v185
	v_cvt_pk_bf16_f32 v183, v186, v187
	v_cvt_pk_bf16_f32 v184, v188, v240
	v_cvt_pk_bf16_f32 v185, v241, v244
	s_nop 0
	v_permlane32_swap_b32_e32 v150, v152
	v_permlane32_swap_b32_e32 v151, v153
	v_permlane32_swap_b32_e32 v172, v174
	v_permlane32_swap_b32_e32 v173, v175
	v_permlane32_swap_b32_e32 v176, v178
	v_permlane32_swap_b32_e32 v177, v179
	v_permlane32_swap_b32_e32 v182, v184
	v_permlane32_swap_b32_e32 v183, v185
	v_add_u32_e32 v170, s54, v227
	ds_read_b64_tr_b16 v[186:187], v170 offset:0
	ds_read_b64_tr_b16 v[188:189], v170 offset:0x800
	ds_read_b64_tr_b16 v[230:231], v170 offset:0x1000
	ds_read_b64_tr_b16 v[232:233], v170 offset:0x1800
	ds_read_b64_tr_b16 v[234:235], v170 offset:0x2000
	ds_read_b64_tr_b16 v[236:237], v170 offset:0x2800
	ds_read_b64_tr_b16 v[238:239], v170 offset:0x3000
	ds_read_b64_tr_b16 v[240:241], v170 offset:0x3800
	s_waitcnt lgkmcnt(0)
	s_nop 0
	v_mfma_f32_32x32x16_bf16 v[0:15], v[150:153], v[186:189], v[0:15]
	ds_read_b64_tr_b16 v[186:187], v170 offset:0x200
	ds_read_b64_tr_b16 v[188:189], v170 offset:0xa00
	v_mfma_f32_32x32x16_bf16 v[0:15], v[172:175], v[230:233], v[0:15]
	ds_read_b64_tr_b16 v[230:231], v170 offset:0x1200
	ds_read_b64_tr_b16 v[232:233], v170 offset:0x1a00
	v_mfma_f32_32x32x16_bf16 v[0:15], v[176:179], v[234:237], v[0:15]
	ds_read_b64_tr_b16 v[234:235], v170 offset:0x2200
	ds_read_b64_tr_b16 v[236:237], v170 offset:0x2a00
	v_mfma_f32_32x32x16_bf16 v[0:15], v[182:185], v[238:241], v[0:15]
	ds_read_b64_tr_b16 v[238:239], v170 offset:0x3200
	ds_read_b64_tr_b16 v[240:241], v170 offset:0x3a00
	s_waitcnt lgkmcnt(0)
	v_mfma_f32_32x32x16_bf16 v[48:63], v[150:153], v[186:189], v[48:63]
	ds_read_b64_tr_b16 v[186:187], v170 offset:0x400
	ds_read_b64_tr_b16 v[188:189], v170 offset:0xc00
	v_mfma_f32_32x32x16_bf16 v[48:63], v[172:175], v[230:233], v[48:63]
	ds_read_b64_tr_b16 v[230:231], v170 offset:0x1400
	ds_read_b64_tr_b16 v[232:233], v170 offset:0x1c00
	v_mfma_f32_32x32x16_bf16 v[48:63], v[176:179], v[234:237], v[48:63]
	ds_read_b64_tr_b16 v[234:235], v170 offset:0x2400
	ds_read_b64_tr_b16 v[236:237], v170 offset:0x2c00
	v_mfma_f32_32x32x16_bf16 v[48:63], v[182:185], v[238:241], v[48:63]
	ds_read_b64_tr_b16 v[238:239], v170 offset:0x3400
	ds_read_b64_tr_b16 v[240:241], v170 offset:0x3c00
	s_waitcnt lgkmcnt(0)
	v_mfma_f32_32x32x16_bf16 v[32:47], v[150:153], v[186:189], v[32:47]
	ds_read_b64_tr_b16 v[186:187], v170 offset:0x600
	ds_read_b64_tr_b16 v[188:189], v170 offset:0xe00
	v_mfma_f32_32x32x16_bf16 v[32:47], v[172:175], v[230:233], v[32:47]
	ds_read_b64_tr_b16 v[230:231], v170 offset:0x1600
	ds_read_b64_tr_b16 v[232:233], v170 offset:0x1e00
	v_mfma_f32_32x32x16_bf16 v[32:47], v[176:179], v[234:237], v[32:47]
	ds_read_b64_tr_b16 v[234:235], v170 offset:0x2600
	ds_read_b64_tr_b16 v[236:237], v170 offset:0x2e00
	v_mfma_f32_32x32x16_bf16 v[32:47], v[182:185], v[238:241], v[32:47]
	ds_read_b64_tr_b16 v[238:239], v170 offset:0x3600
	ds_read_b64_tr_b16 v[240:241], v170 offset:0x3e00
	s_waitcnt lgkmcnt(0)
	v_mfma_f32_32x32x16_bf16 v[16:31], v[150:153], v[186:189], v[16:31]
	v_max_f32_e32 v151, v146, v146
	v_max_f32_e32 v145, v151, v145
	v_sub_f32_e32 v151, v146, v145
	v_mul_f32_e32 v151, 0x3dd53b94, v151
	v_sub_f32_e32 v150, s7, v146
	v_exp_f32_e32 v151, v151
	v_cmp_ge_f32_e32 vcc, s0, v150
	v_mfma_f32_32x32x16_bf16 v[16:31], v[172:175], v[230:233], v[16:31]
	s_cmp_eq_u64 vcc, exec
	s_cselect_b64 s[48:49], -1, 0
	v_cndmask_b32_e64 v170, v151, 1.0, s[48:49]
	v_cmp_gt_f32_e32 vcc, 1.0, v170
	v_mfma_f32_32x32x16_bf16 v[16:31], v[176:179], v[234:237], v[16:31]
	v_mfma_f32_32x32x16_bf16 v[16:31], v[182:185], v[238:241], v[16:31]
	s_cbranch_vccz .LBB0_188
	s_and_saveexec_b64 s[22:23], s[42:43]
	ds_write_b32 v157, v170 offset:128
	s_or_b64 exec, exec, s[22:23]
	s_waitcnt lgkmcnt(0)
	v_add_u32_e32 v182, s89, v148
	ds_read_b128 v[150:153], v182 offset:224
	ds_read_b128 v[172:175], v182 offset:192
	ds_read_b128 v[176:179], v182 offset:160
	ds_read_b128 v[182:185], v182 offset:128
	s_waitcnt lgkmcnt(0)
	v_pk_mul_f32 v[12:13], v[12:13], v[150:151]
	v_pk_mul_f32 v[8:9], v[8:9], v[172:173]
	v_pk_mul_f32 v[4:5], v[4:5], v[176:177]
	v_pk_mul_f32 v[14:15], v[14:15], v[152:153]
	v_pk_mul_f32 v[10:11], v[10:11], v[174:175]
	v_pk_mul_f32 v[6:7], v[6:7], v[178:179]
	v_pk_mul_f32 v[2:3], v[2:3], v[184:185]
	v_pk_mul_f32 v[0:1], v[0:1], v[182:183]
	v_pk_mul_f32 v[60:61], v[60:61], v[150:151]
	v_pk_mul_f32 v[56:57], v[56:57], v[172:173]
	v_pk_mul_f32 v[52:53], v[52:53], v[176:177]
	v_pk_mul_f32 v[62:63], v[62:63], v[152:153]
	v_pk_mul_f32 v[58:59], v[58:59], v[174:175]
	v_pk_mul_f32 v[54:55], v[54:55], v[178:179]
	v_pk_mul_f32 v[50:51], v[50:51], v[184:185]
	v_pk_mul_f32 v[48:49], v[48:49], v[182:183]
	v_pk_mul_f32 v[44:45], v[44:45], v[150:151]
	v_pk_mul_f32 v[40:41], v[40:41], v[172:173]
	v_pk_mul_f32 v[36:37], v[36:37], v[176:177]
	v_pk_mul_f32 v[46:47], v[46:47], v[152:153]
	v_pk_mul_f32 v[42:43], v[42:43], v[174:175]
	v_pk_mul_f32 v[38:39], v[38:39], v[178:179]
	v_pk_mul_f32 v[34:35], v[34:35], v[184:185]
	v_pk_mul_f32 v[32:33], v[32:33], v[182:183]
	v_pk_mul_f32 v[28:29], v[28:29], v[150:151]
	v_pk_mul_f32 v[24:25], v[24:25], v[172:173]
	v_pk_mul_f32 v[20:21], v[20:21], v[176:177]
	v_pk_mul_f32 v[30:31], v[30:31], v[152:153]
	v_pk_mul_f32 v[26:27], v[26:27], v[174:175]
	v_pk_mul_f32 v[22:23], v[22:23], v[178:179]
	v_pk_mul_f32 v[18:19], v[18:19], v[184:185]
	v_pk_mul_f32 v[16:17], v[16:17], v[182:183]

; __device__ __forceinline__ int opaque_tid(int wave_s) { int l; asm volatile("v_mbcnt_lo_u32_b32 %0, -1, 0\n\tv_mbcnt_hi_u32_b32 %0, -1, %0" : "=v"(l)); return (wave_s << 6) | l; }
; #define LAS __attribute__((address_space(3)))
; __device__ __forceinline__ float bf2f(unsigned short u) { return __uint_as_float((unsigned)u << 16); }
; __device__ __forceinline__ void phase_attn_tail(KA a, LAS unsigned char* lds, int vcu, int G, int wave) {
;     const int tid = opaque_tid(wave), lane = tid & 63;
;     LAS float* qs = (LAS float*)lds;
;     LAS float* sc = (LAS float*)(lds + 16 * 192 * 4);
;     const bf16* Q = (const bf16*)(a->ws + WS_Q); const bf16* K = (const bf16*)(a->ws + WS_K); const bf16* KV = (const bf16*)(a->ws + WS_KVRAW);
;     float* PART = (float*)(a->ws + WS_PART);
;     constexpr float C = att::SCALE * 1.4426950408889634f;
; #pragma unroll 1
;     for (int u = vcu; u < 264; u += G) {
;         const int h = u < 256 ? (u >> 5) : (u - 256), ck = u < 256 ? (u & 31) : 32, k0 = ck * 256, nk = ck < 32 ? 256 : 16;
;         for (int i = tid; i < 16 * 192; i += NTHR) qs[i] = bf2f(Q[((size_t)h * TP + 8192) * QKD + i]);
.LBB0_200:
	v_xor_b32_e32 v205, 1, v196
	v_xor_b32_e32 v206, 2, v196
	v_xor_b32_e32 v207, 4, v196
	v_lshlrev_b32_e32 v205, 2, v205
	v_lshlrev_b32_e32 v206, 2, v206
	v_lshlrev_b32_e32 v207, 2, v207
	v_readlane_b32 s11, v255, 7
	s_cmpk_gt_i32 s11, 0x107
	v_mbcnt_lo_u32_b32 v0, -1, 0
	v_mbcnt_hi_u32_b32 v0, -1, v0
	s_cbranch_scc1 .LBB0_223
	v_readlane_b32 s18, v253, 25
	v_and_b32_e32 v1, 63, v0
	s_movk_i32 s3, 0xff
	v_or_b32_e32 v12, s18, v0
	v_mov_b32_e32 v2, s18
	v_lshl_add_u32 v32, v1, 4, 0
	v_cmp_eq_u32_e64 s[42:43], 0, v1
	v_max_i32_e32 v1, 0xa00, v12
	v_bitop3_b32 v14, v0, s3, v2 bitop3:0xc8
	v_ashrrev_i32_e32 v2, 8, v12
	s_movk_i32 s3, 0x1800
	v_sub_u32_e32 v1, v1, v12
	s_add_u32 s48, s16, 0x2f3a0000
	v_mad_i32_i24 v33, v2, s3, 0
	v_add_u32_e32 v1, 0x1ff, v1
	s_movk_i32 s3, 0x1ff
	s_addc_u32 s49, s17, 0
	v_lshlrev_b32_e32 v3, 13, v2
	v_lshrrev_b32_e32 v2, 9, v1
	v_cmp_lt_u32_e64 s[44:45], s3, v1
	v_lshlrev_b32_e32 v1, 4, v0
	s_add_u32 s7, s16, 0x28310000
	v_and_b32_e32 v148, 0x1f0, v1
	v_and_b32_e32 v0, 31, v0
	v_readlane_b32 s19, v253, 26
	s_addc_u32 s9, s17, 0
	s_movk_i32 s0, 0xc00
	v_add_u32_e32 v2, 1, v2
	v_lshl_add_u64 v[18:19], s[48:49], 0, v[148:149]
	v_lshlrev_b32_e32 v148, 3, v0
	v_cmp_gt_i32_e64 s[40:41], s0, v12
	v_lshlrev_b32_e32 v4, 2, v14
	v_ashrrev_i32_e32 v16, 5, v12
	v_and_b32_e32 v34, 0xfffffe, v2
	v_lshlrev_b32_e32 v36, 2, v12
	s_add_u32 s52, s16, 0x298d0010
	v_readlane_b32 s0, v254, 49
	v_lshl_add_u64 v[0:1], s[16:17], 0, v[148:149]
	s_mov_b64 s[18:19], 0x25f17100
	v_add3_u32 v15, 0, v3, v4
	v_ashrrev_i32_e32 v17, 31, v16
	v_lshl_add_u32 v35, v34, 9, v12
	v_add_u32_e32 v13, 0x200, v12
	v_cmp_ne_u32_e64 s[46:47], v2, v34
	v_add_u32_e32 v37, 0, v36
	s_addc_u32 s53, s17, 0
	v_lshl_add_u32 v38, v16, 10, s0
	v_lshl_add_u64 v[20:21], v[0:1], 0, s[18:19]

; __device__ __forceinline__ float bflo(unsigned w) { return __uint_as_float(w << 16); }
; __device__ __forceinline__ float bfhi(unsigned w) { return __uint_as_float(w & 0xffff0000u); }
; __device__ __forceinline__ void phase_fft(KA a, int l, LAS unsigned char* lds, int vcu, int G, int wave) {
;     ...
; #pragma unroll 2
;         for (int i = 0; i < 4; ++i) { const int j4 = 4 * (tid + 512 * i);
;             const u32x2 wf0 = *(const u32x2*)(hf0 + j4), wf1 = *(const u32x2*)(hf1 + j4), wb0 = *(const u32x2*)(hb0 + j4), wb1 = *(const u32x2*)(hb1 + j4);
;             f32x4 f0 = {bflo(wf0.x), bfhi(wf0.x), bflo(wf0.y), bfhi(wf0.y)}, f1 = {bflo(wf1.x), bfhi(wf1.x), bflo(wf1.y), bfhi(wf1.y)};
;             const f32x4 b0 = {bflo(wb0.x), bfhi(wb0.x), bflo(wb0.y), bfhi(wb0.y)}, b1 = {bflo(wb1.x), bfhi(wb1.x), bflo(wb1.y), bfhi(wb1.y)};
;             if (j4 == 0) { f0.x += a->in[I_SKIP][l * HYW + c0]; f1.x += a->in[I_SKIP][l * HYW + c1]; }
; #pragma unroll
;             for (int e = 0; e < 4; ++e) { const int m = j4 + e; const bool ok = m < LB;
;                 x[fsw(m)] = ok ? (f32x2){f0[e], f1[e]} : (f32x2){0.f, 0.f};
;                 if (m > 0) x[fsw(FN - m)] = ok ? (f32x2){b0[e], b1[e]} : (f32x2){0.f, 0.f}; }
;         }
.LBB0_226:
	s_lshl_b32 s48, s20, 1
	s_mul_i32 s18, s20, 0x4200
	s_mul_hi_i32 s19, s48, 0x2100
	s_or_b32 s3, s48, 1
	s_ashr_i32 s49, s48, 31
	s_lshl_b64 s[44:45], s[18:19], 1
	s_add_u32 s58, s28, s44
	s_addc_u32 s59, s29, s45
	s_add_i32 s54, s48, 0x400
	s_add_i32 s22, s18, 0x840000
	s_mul_hi_i32 s23, s54, 0x2100
	s_ashr_i32 s55, s54, 31
	s_lshl_b64 s[52:53], s[22:23], 1
	s_add_u32 s60, s28, s52
	s_mul_hi_i32 s23, s3, 0x2100
	s_mul_i32 s22, s3, 0x2100
	s_addc_u32 s61, s29, s53
	s_lshl_b64 s[46:47], s[22:23], 1
	s_add_u32 s62, s28, s46
	s_addc_u32 s63, s29, s47
	s_add_i32 s3, s48, 0x401
	s_add_i32 s18, s18, 0x842100
	s_mul_hi_i32 s19, s3, 0x2100
	v_readlane_b32 s0, v253, 25
	s_lshl_b64 s[56:57], s[18:19], 1
	v_mbcnt_lo_u32_b32 v100, -1, 0
	v_mbcnt_hi_u32_b32 v100, -1, v100
	s_add_u32 s64, s28, s56
	v_or_b32_e32 v106, s0, v100
	v_readlane_b32 s0, v255, 9
	s_addc_u32 s65, s29, s57
	s_add_i32 s66, s48, s0
	s_mov_b64 s[38:39], s[90:91]
	s_mov_b32 s90, s51
	s_mov_b32 s51, s67
	v_lshrrev_b32_e32 v36, 2, v106
	s_ashr_i32 s67, s66, 31
	v_lshlrev_b32_e32 v0, 2, v106
	v_lshrrev_b32_e32 v101, 1, v106
	v_and_b32_e32 v1, 16, v36
	s_add_u32 s74, s48, s0
	v_readlane_b32 s0, v255, 14
	s_waitcnt vmcnt(0)
	v_and_or_b32 v14, v101, 14, v1
	s_addc_u32 s75, s49, s0
	s_mov_b32 s7, 0
	v_sub_u32_e32 v15, 0, v0
	v_add_u32_e32 v16, 0x803, v0
	v_readlane_b32 s1, v253, 26
	v_add_u32_e32 v188, 0xfffff7fd, v16
	v_ashrrev_i32_e32 v189, 31, v188
	v_lshlrev_b64 v[188:189], 1, v[188:189]
	v_lshl_add_u64 v[190:191], s[58:59], 0, v[188:189]
	global_load_dwordx2 v[156:157], v[190:191], off
	v_lshl_add_u64 v[190:191], s[62:63], 0, v[188:189]
	global_load_dwordx2 v[158:159], v[190:191], off
	v_lshl_add_u64 v[190:191], s[60:61], 0, v[188:189]
	global_load_dwordx2 v[160:161], v[190:191], off
	v_lshl_add_u64 v[190:191], s[64:65], 0, v[188:189]
	global_load_dwordx2 v[162:163], v[190:191], off
	v_add_u32_e32 v188, 0x7fd, v16
	v_ashrrev_i32_e32 v189, 31, v188
	v_lshlrev_b64 v[188:189], 1, v[188:189]
	v_lshl_add_u64 v[190:191], s[58:59], 0, v[188:189]
	global_load_dwordx2 v[164:165], v[190:191], off
	v_lshl_add_u64 v[190:191], s[62:63], 0, v[188:189]
	global_load_dwordx2 v[166:167], v[190:191], off
	v_lshl_add_u64 v[190:191], s[60:61], 0, v[188:189]
	global_load_dwordx2 v[168:169], v[190:191], off
	v_lshl_add_u64 v[190:191], s[64:65], 0, v[188:189]
	global_load_dwordx2 v[170:171], v[190:191], off
	v_add_u32_e32 v188, 0x17fd, v16
	v_ashrrev_i32_e32 v189, 31, v188
	v_lshlrev_b64 v[188:189], 1, v[188:189]
	v_lshl_add_u64 v[190:191], s[58:59], 0, v[188:189]
	global_load_dwordx2 v[172:173], v[190:191], off
	v_lshl_add_u64 v[190:191], s[62:63], 0, v[188:189]
	global_load_dwordx2 v[174:175], v[190:191], off
	v_lshl_add_u64 v[190:191], s[60:61], 0, v[188:189]
	global_load_dwordx2 v[176:177], v[190:191], off
	v_lshl_add_u64 v[190:191], s[64:65], 0, v[188:189]
	global_load_dwordx2 v[178:179], v[190:191], off
	v_add_u32_e32 v188, 0x27fd, v16
	v_ashrrev_i32_e32 v189, 31, v188
	v_lshlrev_b64 v[188:189], 1, v[188:189]
	v_lshl_add_u64 v[190:191], s[58:59], 0, v[188:189]
	global_load_dwordx2 v[180:181], v[190:191], off
	v_lshl_add_u64 v[190:191], s[62:63], 0, v[188:189]
	global_load_dwordx2 v[182:183], v[190:191], off
	v_lshl_add_u64 v[190:191], s[60:61], 0, v[188:189]
	global_load_dwordx2 v[184:185], v[190:191], off
	v_lshl_add_u64 v[190:191], s[64:65], 0, v[188:189]
	global_load_dwordx2 v[186:187], v[190:191], off
	s_branch .LBB0_228
.LBB0_227:
	s_or_b64 exec, exec, s[22:23]
	s_addk_i32 s7, 0xf000
	s_cmpk_eq_i32 s7, 0xe000
	v_add_u32_e32 v16, 0x1000, v16
	v_mov_b32_e32 v156, v164
	v_mov_b32_e32 v157, v165
	v_mov_b32_e32 v158, v166
	v_mov_b32_e32 v159, v167
	v_mov_b32_e32 v160, v168
	v_mov_b32_e32 v161, v169
	v_mov_b32_e32 v162, v170
	v_mov_b32_e32 v163, v171
	v_mov_b32_e32 v164, v172
	v_mov_b32_e32 v165, v173
	v_mov_b32_e32 v166, v174
	v_mov_b32_e32 v167, v175
	v_mov_b32_e32 v168, v176
	v_mov_b32_e32 v169, v177
	v_mov_b32_e32 v170, v178
	v_mov_b32_e32 v171, v179
	v_mov_b32_e32 v172, v180
	v_mov_b32_e32 v173, v181
	v_mov_b32_e32 v174, v182
	v_mov_b32_e32 v175, v183
	v_mov_b32_e32 v176, v184
	v_mov_b32_e32 v177, v185
	v_mov_b32_e32 v178, v186
	v_mov_b32_e32 v179, v187
	s_cbranch_scc1 .LBB0_248
.LBB0_228:
	v_add_u32_e32 v12, 0xfffff7fd, v16
	v_ashrrev_i32_e32 v13, 31, v12
	v_lshlrev_b64 v[0:1], 1, v[12:13]
	v_lshl_add_u64 v[2:3], s[58:59], 0, v[0:1]
	v_lshl_add_u64 v[4:5], s[62:63], 0, v[0:1]
	s_waitcnt vmcnt(0)
	v_mov_b32_e32 v2, v156
	v_mov_b32_e32 v3, v157
	v_lshl_add_u64 v[6:7], s[60:61], 0, v[0:1]
	v_mov_b32_e32 v4, v158
	v_mov_b32_e32 v5, v159
	v_lshl_add_u64 v[0:1], s[64:65], 0, v[0:1]
	v_mov_b32_e32 v8, v160
	v_mov_b32_e32 v9, v161
	v_mov_b32_e32 v10, v162
	v_mov_b32_e32 v11, v163
	v_add_u32_e32 v17, s7, v15
	v_cmp_eq_u32_e32 vcc, 0, v17
	s_waitcnt vmcnt(0)
	v_lshlrev_b32_e32 v0, 16, v2
	v_and_b32_e32 v1, 0xffff0000, v2
	v_lshlrev_b32_e32 v2, 16, v3
	v_and_b32_e32 v3, 0xffff0000, v3
	v_lshlrev_b32_e32 v6, 16, v4
	v_and_b32_e32 v7, 0xffff0000, v4
	v_lshlrev_b32_e32 v4, 16, v5
	v_and_b32_e32 v5, 0xffff0000, v5
	s_and_saveexec_b64 s[22:23], vcc
	s_cbranch_execz .LBB0_230
	s_load_dwordx2 s[18:19], s[36:37], 0x98
	s_lshl_b64 s[24:25], s[66:67], 2
	s_waitcnt lgkmcnt(0)
	s_add_u32 s24, s18, s24
	s_addc_u32 s25, s19, s25
	global_load_dword v13, v149, s[24:25]
	s_lshl_b64 s[24:25], s[74:75], 2
	s_add_u32 s18, s18, s24
	s_addc_u32 s19, s19, s25
	s_waitcnt vmcnt(0)
	v_add_f32_e32 v0, v13, v0
	global_load_dword v13, v149, s[18:19] offset:4
	s_waitcnt vmcnt(0)
	v_add_f32_e32 v6, v13, v6

; __device__ __forceinline__ f32x2 cmul(f32x2 a, f32x2 w) { return (f32x2){a.x * w.x - a.y * w.y, a.x * w.y + a.y * w.x}; }
; __device__ __forceinline__ void fft_inv(LAS f32x2* x, int tid) {
;     ...
; #pragma unroll 2
;     for (int i = 0; i < 8; ++i) {
;         const int j = tid + 512 * i;
;         const float f = (float)j * (1.0f / 16384.0f);
;         const f32x2 w1 = {__builtin_amdgcn_cosf(f), __builtin_amdgcn_sinf(f)}; const f32x2 w2 = cmul(w1, w1), w3 = cmul(w2, w1);
;         f32x2 a0 = x[fsw(j)], a1 = cmul(x[fsw(j + 4096)], w1), a2 = cmul(x[fsw(j + 8192)], w2), a3 = cmul(x[fsw(j + 12288)], w3);
;         r4<true>(a0, a1, a2, a3);
;         x[fsw(j)] = a0; x[fsw(j + 4096)] = a1; x[fsw(j + 8192)] = a2; x[fsw(j + 12288)] = a3;
;     }
;     __syncthreads();
.LBB0_338:
	v_add_u32_e32 v1, s7, v36
	v_cvt_f32_i32_e32 v2, v1
	v_add_u32_e32 v14, 0x1000, v1
	v_xor_b32_e32 v12, v1, v0
	v_xor_b32_e32 v14, v14, v0
	v_mul_f32_e32 v3, 0x38800000, v2
	v_cos_f32_e32 v2, v3
	v_sin_f32_e32 v3, v3
	v_lshl_add_u32 v20, v12, 3, 0
	v_lshl_add_u32 v21, v14, 3, 0
	ds_read_b64 v[12:13], v20
	ds_read_b64 v[14:15], v21
	v_pk_mul_f32 v[4:5], v[2:3], v[2:3] op_sel:[1,1] op_sel_hi:[0,1]
	v_pk_fma_f32 v[6:7], v[2:3], v[2:3], v[4:5] op_sel_hi:[0,1,1] neg_lo:[0,0,1] neg_hi:[0,0,1]
	v_pk_fma_f32 v[4:5], v[2:3], v[2:3], v[4:5] op_sel_hi:[0,1,1]
	v_mov_b32_e32 v16, v3
	v_mov_b32_e32 v8, v6
	v_mov_b32_e32 v9, v5
	s_waitcnt lgkmcnt(0)
	v_pk_mul_f32 v[16:17], v[14:15], v[16:17] op_sel:[1,0] op_sel_hi:[0,0]
	v_pk_mul_f32 v[10:11], v[2:3], v[8:9]
	v_pk_mul_f32 v[8:9], v[2:3], v[8:9] op_sel:[1,0] op_sel_hi:[0,1]
	v_pk_fma_f32 v[18:19], v[14:15], v[2:3], v[16:17] neg_lo:[0,0,1] neg_hi:[0,0,1]
	v_pk_fma_f32 v[2:3], v[14:15], v[2:3], v[16:17] op_sel_hi:[1,0,1]
	s_addk_i32 s7, 0x400
	v_add_u32_e32 v2, 0x2000, v1
	v_xor_b32_e32 v2, v2, v0
	v_lshl_add_u32 v16, v2, 3, 0
	v_mov_b32_e32 v19, v3
	ds_read_b64 v[2:3], v16
	s_cmpk_lg_i32 s7, 0x1000
	s_waitcnt lgkmcnt(0)
	v_pk_mul_f32 v[4:5], v[2:3], v[4:5] op_sel:[1,1] op_sel_hi:[0,1]
	v_pk_fma_f32 v[14:15], v[2:3], v[6:7], v[4:5] neg_lo:[0,0,1] neg_hi:[0,0,1]
	v_pk_fma_f32 v[2:3], v[2:3], v[6:7], v[4:5] op_sel_hi:[1,0,1]
	v_pk_add_f32 v[4:5], v[8:9], v[8:9] op_sel:[0,1] op_sel_hi:[0,1]
	v_add_u32_e32 v2, 0x3000, v1
	v_xor_b32_e32 v2, v2, v0
	v_lshl_add_u32 v17, v2, 3, 0
	v_mov_b32_e32 v15, v3
	ds_read_b64 v[2:3], v17
	v_pk_add_f32 v[6:7], v[10:11], v[10:11] op_sel:[0,1] op_sel_hi:[0,1] neg_lo:[0,1] neg_hi:[0,1]
	s_waitcnt lgkmcnt(0)
	v_pk_mul_f32 v[4:5], v[2:3], v[4:5] op_sel:[1,0] op_sel_hi:[0,1]
	v_pk_fma_f32 v[8:9], v[2:3], v[6:7], v[4:5] neg_lo:[0,0,1] neg_hi:[0,0,1]
	v_pk_fma_f32 v[2:3], v[2:3], v[6:7], v[4:5]
	v_pk_add_f32 v[4:5], v[12:13], v[14:15] neg_lo:[0,1] neg_hi:[0,1]
	v_mov_b32_e32 v9, v3
	v_pk_add_f32 v[6:7], v[18:19], v[8:9]
	v_pk_add_f32 v[8:9], v[18:19], v[8:9] neg_lo:[0,1] neg_hi:[0,1]
	v_pk_add_f32 v[2:3], v[12:13], v[14:15]
	v_xor_b32_e32 v10, 0x80000000, v9
	v_mov_b32_e32 v11, v8
	v_pk_add_f32 v[8:9], v[2:3], v[6:7]
	v_pk_add_f32 v[12:13], v[4:5], v[10:11]
	v_pk_add_f32 v[2:3], v[2:3], v[6:7] neg_lo:[0,1] neg_hi:[0,1]
	v_pk_add_f32 v[4:5], v[4:5], v[10:11] neg_lo:[0,1] neg_hi:[0,1]
	ds_write_b64 v20, v[8:9]
	ds_write_b64 v21, v[12:13]
	ds_write_b64 v16, v[2:3]
	ds_write_b64 v17, v[4:5]
	v_add_u32_e32 v12, 0x200, v1
	v_cvt_f32_i32_e32 v2, v12
	v_add_u32_e32 v14, 0x1200, v1
	v_xor_b32_e32 v12, v12, v0
	v_xor_b32_e32 v14, v14, v0
	v_mul_f32_e32 v3, 0x38800000, v2
	v_cos_f32_e32 v2, v3
	v_sin_f32_e32 v3, v3
	v_lshl_add_u32 v20, v12, 3, 0
	v_lshl_add_u32 v21, v14, 3, 0
	ds_read_b64 v[12:13], v20
	ds_read_b64 v[14:15], v21
	v_pk_mul_f32 v[4:5], v[2:3], v[2:3] op_sel:[1,1] op_sel_hi:[0,1]
	v_pk_fma_f32 v[6:7], v[2:3], v[2:3], v[4:5] op_sel_hi:[0,1,1] neg_lo:[0,0,1] neg_hi:[0,0,1]
	v_pk_fma_f32 v[4:5], v[2:3], v[2:3], v[4:5] op_sel_hi:[0,1,1]
	v_mov_b32_e32 v16, v3
	v_mov_b32_e32 v8, v6
	v_mov_b32_e32 v9, v5
	s_waitcnt lgkmcnt(0)
	v_pk_mul_f32 v[16:17], v[14:15], v[16:17] op_sel:[1,0] op_sel_hi:[0,0]
	v_pk_mul_f32 v[10:11], v[2:3], v[8:9]
	v_pk_mul_f32 v[8:9], v[2:3], v[8:9] op_sel:[1,0] op_sel_hi:[0,1]
	v_pk_fma_f32 v[18:19], v[14:15], v[2:3], v[16:17] neg_lo:[0,0,1] neg_hi:[0,0,1]
	v_pk_fma_f32 v[2:3], v[14:15], v[2:3], v[16:17] op_sel_hi:[1,0,1]
	s_nop 0
	v_add_u32_e32 v2, 0x2200, v1
	v_xor_b32_e32 v2, v2, v0
	v_lshl_add_u32 v16, v2, 3, 0
	v_mov_b32_e32 v19, v3
	ds_read_b64 v[2:3], v16
	v_add_u32_e32 v1, 0x3200, v1
	v_xor_b32_e32 v1, v1, v0
	v_lshl_add_u32 v1, v1, 3, 0
	s_waitcnt lgkmcnt(0)
	v_pk_mul_f32 v[4:5], v[2:3], v[4:5] op_sel:[1,1] op_sel_hi:[0,1]
	v_pk_fma_f32 v[14:15], v[2:3], v[6:7], v[4:5] neg_lo:[0,0,1] neg_hi:[0,0,1]
	v_pk_fma_f32 v[2:3], v[2:3], v[6:7], v[4:5] op_sel_hi:[1,0,1]
	v_pk_add_f32 v[4:5], v[8:9], v[8:9] op_sel:[0,1] op_sel_hi:[0,1]
	v_mov_b32_e32 v15, v3
	ds_read_b64 v[2:3], v1
	v_pk_add_f32 v[6:7], v[10:11], v[10:11] op_sel:[0,1] op_sel_hi:[0,1] neg_lo:[0,1] neg_hi:[0,1]
	s_waitcnt lgkmcnt(0)
	v_pk_mul_f32 v[4:5], v[2:3], v[4:5] op_sel:[1,0] op_sel_hi:[0,1]
	v_pk_fma_f32 v[8:9], v[2:3], v[6:7], v[4:5] neg_lo:[0,0,1] neg_hi:[0,0,1]
	v_pk_fma_f32 v[2:3], v[2:3], v[6:7], v[4:5]
	v_pk_add_f32 v[4:5], v[12:13], v[14:15] neg_lo:[0,1] neg_hi:[0,1]
	v_mov_b32_e32 v9, v3
	v_pk_add_f32 v[2:3], v[12:13], v[14:15]
	v_pk_add_f32 v[6:7], v[18:19], v[8:9]
	v_pk_add_f32 v[8:9], v[18:19], v[8:9] neg_lo:[0,1] neg_hi:[0,1]
	s_nop 0
	v_xor_b32_e32 v10, 0x80000000, v9
	v_mov_b32_e32 v11, v8
	v_pk_add_f32 v[8:9], v[2:3], v[6:7]
	v_pk_add_f32 v[12:13], v[4:5], v[10:11]
	v_pk_add_f32 v[2:3], v[2:3], v[6:7] neg_lo:[0,1] neg_hi:[0,1]
	v_pk_add_f32 v[4:5], v[4:5], v[10:11] neg_lo:[0,1] neg_hi:[0,1]
	ds_write_b64 v20, v[8:9]
	ds_write_b64 v21, v[12:13]
	ds_write_b64 v16, v[2:3]
	ds_write_b64 v1, v[4:5]
	s_cbranch_scc1 .LBB0_338
	s_movk_i32 s3, 0x7c
	v_cmp_gt_i32_e32 vcc, s3, v106
	s_waitcnt lgkmcnt(0)
	s_barrier
	s_and_saveexec_b64 s[42:43], vcc
	v_readlane_b32 s11, v255, 7
	v_readlane_b32 s66, v255, 8
	s_cbranch_execz .LBB0_353
; #define LAS __attribute__((address_space(3)))
; __device__ __forceinline__ void phase_fft(KA a, int l, LAS unsigned char* lds, int vcu, int G, int wave) {
;     ...
;         if (tid < 124) {
;             const int ch = tid >= 62, u = tid - 62 * ch; const LAS float* hfl = cf + 64 * ch; const LAS float* hbl = hfl + 32; const LAS float* zl = zb + 64 * ch; const LAS float* zh = zl + 32;
;             float s = 0.f; int t;
;             if (u < 31) { t = LB + u; for (int lg = 0; lg <= u; ++lg) s += hfl[lg] * zl[u - lg]; }
;             else { t = u - 31; for (int lg = 0; lg <= 30 - t; ++lg) s += hbl[lg] * zh[t + lg]; }
;             LAS float* xp = (LAS float*)(x + fsw(t)) + ch; *xp += s * (float)FN;
	v_cmp_lt_i32_e32 vcc, 61, v106
	v_not_b32_e32 v0, 61
	s_nop 0
	v_cndmask_b32_e32 v0, 0, v0, vcc
	v_add_u32_e32 v1, v0, v106
	v_cndmask_b32_e64 v2, 0, 64, vcc
	v_lshlrev_b32_e32 v2, 2, v2
	v_cmp_lt_i32_e64 s[40:41], 30, v1
	v_sub_u32_e32 v156, 62, v1
	v_add_u32_e32 v157, 1, v1
	s_mov_b32 s3, 0x20200
	v_cndmask_b32_e64 v156, v157, v156, s[40:41]
	v_cndmask_b32_e64 v157, 0, 32, s[40:41]
	v_lshlrev_b32_e32 v157, 2, v157
	v_add3_u32 v157, v157, v2, s3
	v_cndmask_b32_e64 v158, 0, 1, s[40:41]
	v_add_u32_e32 v158, v158, v1
	s_mov_b32 s3, 0x20000
	v_lshlrev_b32_e32 v158, 2, v158
	v_add3_u32 v158, v158, v2, s3
	v_cndmask_b32_e64 v159, -4, 4, s[40:41]
	v_add_u32_e32 v3, 0x1ff1, v1
	v_subrev_u32_e32 v160, 31, v1
	v_cndmask_b32_e64 v3, v3, v160, s[40:41]
	v_mov_b32_e32 v0, 0
	s_mov_b64 s[22:23], exec
	v_cmp_gt_u32_e64 s[40:41], v156, 0
	s_nop 1
	s_and_b64 exec, s[22:23], s[40:41]
	ds_read_b32 v170, v157 offset:0
	ds_read_b32 v171, v158
	v_add_u32_e32 v158, v158, v159
	ds_read_b32 v172, v157 offset:4
	ds_read_b32 v173, v158
	v_add_u32_e32 v158, v158, v159
	ds_read_b32 v174, v157 offset:8
	ds_read_b32 v175, v158
	v_add_u32_e32 v158, v158, v159
	ds_read_b32 v176, v157 offset:12
	ds_read_b32 v177, v158
	v_add_u32_e32 v158, v158, v159
	ds_read_b32 v178, v157 offset:16
	ds_read_b32 v179, v158
	v_add_u32_e32 v158, v158, v159
	ds_read_b32 v180, v157 offset:20
	ds_read_b32 v181, v158
	v_add_u32_e32 v158, v158, v159
	ds_read_b32 v182, v157 offset:24
	ds_read_b32 v183, v158
	v_add_u32_e32 v158, v158, v159
	ds_read_b32 v184, v157 offset:28
	ds_read_b32 v185, v158
	v_add_u32_e32 v158, v158, v159
	s_waitcnt lgkmcnt(0)
	v_fmac_f32_e32 v0, v170, v171
	v_cmp_gt_u32_e64 s[40:41], v156, 1
	s_nop 1
	s_and_b64 exec, s[22:23], s[40:41]
	v_fmac_f32_e32 v0, v172, v173
	v_cmp_gt_u32_e64 s[40:41], v156, 2
	s_nop 1
	s_and_b64 exec, s[22:23], s[40:41]
	v_fmac_f32_e32 v0, v174, v175
	v_cmp_gt_u32_e64 s[40:41], v156, 3
	s_nop 1
	s_and_b64 exec, s[22:23], s[40:41]
	v_fmac_f32_e32 v0, v176, v177
	v_cmp_gt_u32_e64 s[40:41], v156, 4
	s_nop 1
	s_and_b64 exec, s[22:23], s[40:41]
	v_fmac_f32_e32 v0, v178, v179
	v_cmp_gt_u32_e64 s[40:41], v156, 5
	s_nop 1
	s_and_b64 exec, s[22:23], s[40:41]
	v_fmac_f32_e32 v0, v180, v181
	v_cmp_gt_u32_e64 s[40:41], v156, 6
	s_nop 1
	s_and_b64 exec, s[22:23], s[40:41]
	v_fmac_f32_e32 v0, v182, v183
	v_cmp_gt_u32_e64 s[40:41], v156, 7
	s_nop 1
	s_and_b64 exec, s[22:23], s[40:41]
	v_fmac_f32_e32 v0, v184, v185
	v_cmp_gt_u32_e64 s[40:41], v156, 8
	s_nop 1
	s_and_b64 exec, s[22:23], s[40:41]
	ds_read_b32 v170, v157 offset:32
	ds_read_b32 v171, v158
	v_add_u32_e32 v158, v158, v159
	ds_read_b32 v172, v157 offset:36
	ds_read_b32 v173, v158
	v_add_u32_e32 v158, v158, v159
	ds_read_b32 v174, v157 offset:40
	ds_read_b32 v175, v158
	v_add_u32_e32 v158, v158, v159
	ds_read_b32 v176, v157 offset:44
	ds_read_b32 v177, v158
	v_add_u32_e32 v158, v158, v159
	ds_read_b32 v178, v157 offset:48
	ds_read_b32 v179, v158
	v_add_u32_e32 v158, v158, v159
	ds_read_b32 v180, v157 offset:52
	ds_read_b32 v181, v158
	v_add_u32_e32 v158, v158, v159
	ds_read_b32 v182, v157 offset:56
	ds_read_b32 v183, v158
	v_add_u32_e32 v158, v158, v159
	ds_read_b32 v184, v157 offset:60
	ds_read_b32 v185, v158
	v_add_u32_e32 v158, v158, v159
	s_waitcnt lgkmcnt(0)
; #define LAS __attribute__((address_space(3)))
; __device__ __forceinline__ void phase_fft(KA a, int l, LAS unsigned char* lds, int vcu, int G, int wave) {
;     ...
;         if (tid < 124) {
;             const int ch = tid >= 62, u = tid - 62 * ch; const LAS float* hfl = cf + 64 * ch; const LAS float* hbl = hfl + 32; const LAS float* zl = zb + 64 * ch; const LAS float* zh = zl + 32;
;             float s = 0.f; int t;
;             if (u < 31) { t = LB + u; for (int lg = 0; lg <= u; ++lg) s += hfl[lg] * zl[u - lg]; }
;             else { t = u - 31; for (int lg = 0; lg <= 30 - t; ++lg) s += hbl[lg] * zh[t + lg]; }
;             LAS float* xp = (LAS float*)(x + fsw(t)) + ch; *xp += s * (float)FN;
	v_fmac_f32_e32 v0, v170, v171
	v_cmp_gt_u32_e64 s[40:41], v156, 9
	s_nop 1
	s_and_b64 exec, s[22:23], s[40:41]
	v_fmac_f32_e32 v0, v172, v173
	v_cmp_gt_u32_e64 s[40:41], v156, 10
	s_nop 1
	s_and_b64 exec, s[22:23], s[40:41]
	v_fmac_f32_e32 v0, v174, v175
	v_cmp_gt_u32_e64 s[40:41], v156, 11
	s_nop 1
	s_and_b64 exec, s[22:23], s[40:41]
	v_fmac_f32_e32 v0, v176, v177
	v_cmp_gt_u32_e64 s[40:41], v156, 12
	s_nop 1
	s_and_b64 exec, s[22:23], s[40:41]
	v_fmac_f32_e32 v0, v178, v179
	v_cmp_gt_u32_e64 s[40:41], v156, 13
	s_nop 1
	s_and_b64 exec, s[22:23], s[40:41]
	v_fmac_f32_e32 v0, v180, v181
	v_cmp_gt_u32_e64 s[40:41], v156, 14
	s_nop 1
	s_and_b64 exec, s[22:23], s[40:41]
	v_fmac_f32_e32 v0, v182, v183
	v_cmp_gt_u32_e64 s[40:41], v156, 15
	s_nop 1
	s_and_b64 exec, s[22:23], s[40:41]
	v_fmac_f32_e32 v0, v184, v185
	v_cmp_gt_u32_e64 s[40:41], v156, 16
	s_nop 1
	s_and_b64 exec, s[22:23], s[40:41]
	ds_read_b32 v170, v157 offset:64
	ds_read_b32 v171, v158
	v_add_u32_e32 v158, v158, v159
	ds_read_b32 v172, v157 offset:68
	ds_read_b32 v173, v158
	v_add_u32_e32 v158, v158, v159
	ds_read_b32 v174, v157 offset:72
	ds_read_b32 v175, v158
	v_add_u32_e32 v158, v158, v159
	ds_read_b32 v176, v157 offset:76
	ds_read_b32 v177, v158
	v_add_u32_e32 v158, v158, v159
	ds_read_b32 v178, v157 offset:80
	ds_read_b32 v179, v158
	v_add_u32_e32 v158, v158, v159
	ds_read_b32 v180, v157 offset:84
	ds_read_b32 v181, v158
	v_add_u32_e32 v158, v158, v159
	ds_read_b32 v182, v157 offset:88
	ds_read_b32 v183, v158
	v_add_u32_e32 v158, v158, v159
	ds_read_b32 v184, v157 offset:92
	ds_read_b32 v185, v158
	v_add_u32_e32 v158, v158, v159
	s_waitcnt lgkmcnt(0)
	v_fmac_f32_e32 v0, v170, v171
	v_cmp_gt_u32_e64 s[40:41], v156, 17
	s_nop 1
	s_and_b64 exec, s[22:23], s[40:41]
	v_fmac_f32_e32 v0, v172, v173
	v_cmp_gt_u32_e64 s[40:41], v156, 18
	s_nop 1
	s_and_b64 exec, s[22:23], s[40:41]
	v_fmac_f32_e32 v0, v174, v175
	v_cmp_gt_u32_e64 s[40:41], v156, 19
	s_nop 1
	s_and_b64 exec, s[22:23], s[40:41]
	v_fmac_f32_e32 v0, v176, v177
	v_cmp_gt_u32_e64 s[40:41], v156, 20
	s_nop 1
	s_and_b64 exec, s[22:23], s[40:41]
	v_fmac_f32_e32 v0, v178, v179
	v_cmp_gt_u32_e64 s[40:41], v156, 21
	s_nop 1
	s_and_b64 exec, s[22:23], s[40:41]
	v_fmac_f32_e32 v0, v180, v181
	v_cmp_gt_u32_e64 s[40:41], v156, 22
	s_nop 1
	s_and_b64 exec, s[22:23], s[40:41]
	v_fmac_f32_e32 v0, v182, v183
	v_cmp_gt_u32_e64 s[40:41], v156, 23
	s_nop 1
	s_and_b64 exec, s[22:23], s[40:41]
	v_fmac_f32_e32 v0, v184, v185
	v_cmp_gt_u32_e64 s[40:41], v156, 24
	s_nop 1
	s_and_b64 exec, s[22:23], s[40:41]
	ds_read_b32 v170, v157 offset:96
	ds_read_b32 v171, v158
	v_add_u32_e32 v158, v158, v159
	ds_read_b32 v172, v157 offset:100
	ds_read_b32 v173, v158
	v_add_u32_e32 v158, v158, v159
	ds_read_b32 v174, v157 offset:104
	ds_read_b32 v175, v158
	v_add_u32_e32 v158, v158, v159
	ds_read_b32 v176, v157 offset:108
	ds_read_b32 v177, v158
	v_add_u32_e32 v158, v158, v159
	ds_read_b32 v178, v157 offset:112
	ds_read_b32 v179, v158
	v_add_u32_e32 v158, v158, v159
	ds_read_b32 v180, v157 offset:116
	ds_read_b32 v181, v158
	v_add_u32_e32 v158, v158, v159
	ds_read_b32 v182, v157 offset:120
	ds_read_b32 v183, v158
	v_add_u32_e32 v158, v158, v159
	s_waitcnt lgkmcnt(0)
	v_fmac_f32_e32 v0, v170, v171
	v_cmp_gt_u32_e64 s[40:41], v156, 25
	s_nop 1
	s_and_b64 exec, s[22:23], s[40:41]
	v_fmac_f32_e32 v0, v172, v173
	v_cmp_gt_u32_e64 s[40:41], v156, 26
	s_nop 1
	s_and_b64 exec, s[22:23], s[40:41]
	v_fmac_f32_e32 v0, v174, v175
	v_cmp_gt_u32_e64 s[40:41], v156, 27
	s_nop 1
	s_and_b64 exec, s[22:23], s[40:41]
	v_fmac_f32_e32 v0, v176, v177
	v_cmp_gt_u32_e64 s[40:41], v156, 28
	s_nop 1
	s_and_b64 exec, s[22:23], s[40:41]
	v_fmac_f32_e32 v0, v178, v179
	v_cmp_gt_u32_e64 s[40:41], v156, 29
	s_nop 1
	s_and_b64 exec, s[22:23], s[40:41]
	v_fmac_f32_e32 v0, v180, v181
	v_cmp_gt_u32_e64 s[40:41], v156, 30
	s_nop 1
	s_and_b64 exec, s[22:23], s[40:41]
	v_fmac_f32_e32 v0, v182, v183
	s_mov_b64 exec, s[22:23]

; #define LAS __attribute__((address_space(3)))
; __device__ __forceinline__ unsigned pk2(float lo, float hi) { return pg8::cvt_pk_bf16(lo, hi); }
; template <int NCH, class RB, class EP>
; __device__ __forceinline__ void tail_gemm(const bf16* A16, const bf16* Bt, int K, int ngroups, int vcu, int G, LAS unsigned char* lds, int wave, RB rb, EP ep) {
;     ...
; #pragma unroll 1
;     for (int g = vcu; g < ngroups; g += G) {
;         f32x4 acc[NCH];
; #pragma unroll
;         for (int c = 0; c < NCH; ++c) acc[c] = (f32x4){0.f, 0.f, 0.f, 0.f};
;         const bf16* ap = A16 + (size_t)r * K + wave * kw + 8 * q;
; #pragma unroll 2
;         for (int k = 0; k < kw; k += 32) {
;             const bf16x8 av = *(const bf16x8*)(ap + k);
; #pragma unroll
;             for (int c = 0; c < NCH; ++c) { const bf16x8 bv = *(const bf16x8*)(Bt + (size_t)(rb(g, c) + r) * K + wave * kw + 8 * q + k);
;                 acc[c] = __builtin_amdgcn_mfma_f32_16x16x32_bf16(av, bv, acc[c], 0, 0, 0); }
;         }
; #pragma unroll
;         for (int c = 0; c < NCH; ++c) *(LAS f32x4*)(red + (wave * NCH + c) * 256 + lane * 4) = acc[c];
;         __syncthreads();
; __global__ void __launch_bounds__(NTHR, 2) mk_fwd(Args a_byval) {
;     ...
;                 { bf16* ATT = (bf16*)(ws + WS_ATT);
;                   for (int rep = 0; rep < DUP_TAIL; ++rep)
;                   tail_gemm<1>((const bf16*)(ws + WS_HN) + (size_t)8192 * DM, (const bf16*)(wl + OFF_WINA), DM, ATTC / 16, vcu, G, lds, wave0,
;                       [](int g, int) { return g * 16; }, [=](int g, int r, int c, const float* v) { ATT[(size_t)(8192 + r) * 1024 + g * 16 + c] = (bf16)(pk2(v[0], 0.f) & 0xffffu); }); }
.LBB0_498:
	global_load_dwordx4 v[64:67], v[14:15], off offset:-64
	global_load_dwordx4 v[68:71], v[12:13], off offset:-64
	global_load_dwordx4 v[72:75], v[14:15], off
	global_load_dwordx4 v[76:79], v[12:13], off
	global_load_dwordx4 v[80:83], v[14:15], off offset:64
	global_load_dwordx4 v[84:87], v[12:13], off offset:64
	global_load_dwordx4 v[88:91], v[14:15], off offset:128
	global_load_dwordx4 v[92:95], v[12:13], off offset:128
	global_load_dwordx4 v[96:99], v[14:15], off offset:192
	global_load_dwordx4 v[100:103], v[12:13], off offset:192
	global_load_dwordx4 v[104:107], v[14:15], off offset:256
	global_load_dwordx4 v[108:111], v[12:13], off offset:256
	global_load_dwordx4 v[112:115], v[14:15], off offset:320
	global_load_dwordx4 v[116:119], v[12:13], off offset:320
	global_load_dwordx4 v[120:123], v[14:15], off offset:384
	global_load_dwordx4 v[124:127], v[12:13], off offset:384
	s_waitcnt vmcnt(14)
	v_mfma_f32_16x16x32_bf16 v[0:3], v[64:67], v[68:71], v[0:3]
	s_waitcnt vmcnt(12)
	v_mfma_f32_16x16x32_bf16 v[0:3], v[72:75], v[76:79], v[0:3]
	s_waitcnt vmcnt(10)
	v_mfma_f32_16x16x32_bf16 v[0:3], v[80:83], v[84:87], v[0:3]
	s_waitcnt vmcnt(8)
	v_mfma_f32_16x16x32_bf16 v[0:3], v[88:91], v[92:95], v[0:3]
	s_waitcnt vmcnt(6)
	v_mfma_f32_16x16x32_bf16 v[0:3], v[96:99], v[100:103], v[0:3]
	s_waitcnt vmcnt(4)
	v_mfma_f32_16x16x32_bf16 v[0:3], v[104:107], v[108:111], v[0:3]
	s_waitcnt vmcnt(2)
	v_mfma_f32_16x16x32_bf16 v[0:3], v[112:115], v[116:119], v[0:3]
	s_waitcnt vmcnt(0)
	v_mfma_f32_16x16x32_bf16 v[0:3], v[120:123], v[124:127], v[0:3]
	s_nop 3
	s_nop 6
	ds_write_b128 v16, v[0:3]
	s_waitcnt lgkmcnt(0)
	s_barrier
	s_and_saveexec_b64 s[20:21], vcc
	s_cbranch_execz .LBB0_496
	ds_read2st64_b32 v[0:1], v17 offset1:4
	s_lshl_b32 s18, s7, 4
	s_ashr_i32 s19, s18, 31
	s_waitcnt lgkmcnt(0)
	v_add_f32_e32 v0, 0, v0
	v_add_f32_e32 v2, v0, v1
	ds_read2st64_b32 v[0:1], v17 offset0:8 offset1:12
	s_waitcnt lgkmcnt(0)
	v_add_f32_e32 v0, v2, v0
	v_add_f32_e32 v2, v0, v1
	ds_read2st64_b32 v[0:1], v17 offset0:16 offset1:20
	s_waitcnt lgkmcnt(0)
	v_add_f32_e32 v0, v2, v0
	v_add_f32_e32 v2, v0, v1
	ds_read2st64_b32 v[0:1], v17 offset0:24 offset1:28
	s_waitcnt lgkmcnt(0)
	v_add_f32_e32 v0, v2, v0
	v_add_f32_e32 v0, v0, v1
	v_cvt_pk_bf16_f32 v2, v0, v149
	v_lshl_add_u64 v[0:1], s[18:19], 1, v[4:5]
	global_store_short v[0:1], v2, off
	s_branch .LBB0_496

; #define LAS __attribute__((address_space(3)))
; __device__ __forceinline__ unsigned pk2(float lo, float hi) { return pg8::cvt_pk_bf16(lo, hi); }
; template <int NCH, class RB, class EP>
; __device__ __forceinline__ void tail_gemm(const bf16* A16, const bf16* Bt, int K, int ngroups, int vcu, int G, LAS unsigned char* lds, int wave, RB rb, EP ep) {
;     ...
; #pragma unroll 1
;     for (int g = vcu; g < ngroups; g += G) {
;         f32x4 acc[NCH];
; #pragma unroll
;         for (int c = 0; c < NCH; ++c) acc[c] = (f32x4){0.f, 0.f, 0.f, 0.f};
;         const bf16* ap = A16 + (size_t)r * K + wave * kw + 8 * q;
; #pragma unroll 2
;         for (int k = 0; k < kw; k += 32) {
;             const bf16x8 av = *(const bf16x8*)(ap + k);
; #pragma unroll
;             for (int c = 0; c < NCH; ++c) { const bf16x8 bv = *(const bf16x8*)(Bt + (size_t)(rb(g, c) + r) * K + wave * kw + 8 * q + k);
;                 acc[c] = __builtin_amdgcn_mfma_f32_16x16x32_bf16(av, bv, acc[c], 0, 0, 0); }
;         }
; #pragma unroll
;         for (int c = 0; c < NCH; ++c) *(LAS f32x4*)(red + (wave * NCH + c) * 256 + lane * 4) = acc[c];
;         __syncthreads();
; __global__ void __launch_bounds__(NTHR, 2) mk_fwd(Args a_byval) {
;     ...
;                 { bf16* UT = (bf16*)(ws + WS_UT);
;                   for (int rep = 0; rep < DUP_TAIL; ++rep)
;                   tail_gemm<1>((const bf16*)(ws + WS_HN) + (size_t)8192 * DM, (const bf16*)(wl + OFF_WINH), DM, 3072 / 16, vcu, G, lds, wave0,
;                       [](int g, int) { return g * 16; }, [=](int g, int r, int c, const float* v) { UT[(size_t)(g * 16 + c) * TP + 8192 + r] = (bf16)(pk2(v[0], 0.f) & 0xffffu); }); }
.LBB0_506:
	v_lshl_add_u64 v[20:21], v[14:15], 0, s[30:31]
	v_add_co_u32_e32 v28, vcc, 0x1d800000, v20
	v_lshl_add_u64 v[24:25], v[12:13], 0, s[30:31]
	s_nop 0
	v_addc_co_u32_e32 v29, vcc, 0, v21, vcc
	v_add_co_u32_e32 v30, vcc, 0x400000, v24
	s_nop 1
	v_addc_co_u32_e32 v31, vcc, 0, v25, vcc
	global_load_dwordx4 v[64:67], v[28:29], off
	global_load_dwordx4 v[68:71], v[30:31], off
	global_load_dwordx4 v[72:75], v[28:29], off offset:64
	global_load_dwordx4 v[76:79], v[30:31], off offset:64
	global_load_dwordx4 v[80:83], v[28:29], off offset:128
	global_load_dwordx4 v[84:87], v[30:31], off offset:128
	global_load_dwordx4 v[88:91], v[28:29], off offset:192
	global_load_dwordx4 v[92:95], v[30:31], off offset:192
	global_load_dwordx4 v[96:99], v[28:29], off offset:256
	global_load_dwordx4 v[100:103], v[30:31], off offset:256
	global_load_dwordx4 v[104:107], v[28:29], off offset:320
	global_load_dwordx4 v[108:111], v[30:31], off offset:320
	global_load_dwordx4 v[112:115], v[28:29], off offset:384
	global_load_dwordx4 v[116:119], v[30:31], off offset:384
	global_load_dwordx4 v[120:123], v[28:29], off offset:448
	global_load_dwordx4 v[124:127], v[30:31], off offset:448
	s_waitcnt vmcnt(14)
	v_mfma_f32_16x16x32_bf16 v[0:3], v[64:67], v[68:71], v[0:3]
	s_waitcnt vmcnt(12)
	v_mfma_f32_16x16x32_bf16 v[0:3], v[72:75], v[76:79], v[0:3]
	s_waitcnt vmcnt(10)
	v_mfma_f32_16x16x32_bf16 v[0:3], v[80:83], v[84:87], v[0:3]
	s_waitcnt vmcnt(8)
	v_mfma_f32_16x16x32_bf16 v[0:3], v[88:91], v[92:95], v[0:3]
	s_waitcnt vmcnt(6)
	v_mfma_f32_16x16x32_bf16 v[0:3], v[96:99], v[100:103], v[0:3]
	s_waitcnt vmcnt(4)
	v_mfma_f32_16x16x32_bf16 v[0:3], v[104:107], v[108:111], v[0:3]
	s_waitcnt vmcnt(2)
	v_mfma_f32_16x16x32_bf16 v[0:3], v[112:115], v[116:119], v[0:3]
	s_waitcnt vmcnt(0)
	v_mfma_f32_16x16x32_bf16 v[0:3], v[120:123], v[124:127], v[0:3]
	s_nop 3
	s_nop 6
	ds_write_b128 v16, v[0:3]
	s_waitcnt lgkmcnt(0)
	s_barrier
	s_and_saveexec_b64 s[18:19], s[40:41]
	s_cbranch_execz .LBB0_504
	ds_read2st64_b32 v[0:1], v17 offset1:4
	v_lshl_or_b32 v3, s7, 4, v18
	s_movk_i32 s0, 0x4200
	s_waitcnt lgkmcnt(0)
	v_add_f32_e32 v0, 0, v0
	v_add_f32_e32 v2, v0, v1
	ds_read2st64_b32 v[0:1], v17 offset0:8 offset1:12
	s_waitcnt lgkmcnt(0)
	v_add_f32_e32 v0, v2, v0
	v_add_f32_e32 v2, v0, v1
	ds_read2st64_b32 v[0:1], v17 offset0:16 offset1:20
	s_waitcnt lgkmcnt(0)
	v_add_f32_e32 v0, v2, v0
	v_add_f32_e32 v2, v0, v1
	ds_read2st64_b32 v[0:1], v17 offset0:24 offset1:28
	s_waitcnt lgkmcnt(0)
	v_add_f32_e32 v0, v2, v0
	v_add_f32_e32 v0, v0, v1
	v_cvt_pk_bf16_f32 v2, v0, v149
	v_mov_b64_e32 v[0:1], s[42:43]
	v_mad_i64_i32 v[0:1], s[20:21], v3, s0, v[0:1]
	v_lshl_add_u64 v[0:1], v[4:5], 1, v[0:1]
	v_add_co_u32_e32 v0, vcc, 0x4000, v0
	s_nop 1
	v_addc_co_u32_e32 v1, vcc, 0, v1, vcc
	global_store_short v[0:1], v2, off
	s_branch .LBB0_504
